# v27 + non-temporal (nt) cache hint on the single-use PEER partial sums: P9 PA stores and P10 PA loads
# speedup vs baseline: 1.0069x; 1.0069x over previous
; DI void wave_lds_sync() { asm volatile("s_waitcnt lgkmcnt(0)" ::: "memory"); __builtin_amdgcn_wave_barrier(); }
; DI void phase9(const Params& p, char* smem, int rep) {
;     ...
;       const int tok = __builtin_amdgcn_readfirstlane(c * 16 + w * 4 + t);
;       const int i0 = IDS[(size_t)tok * 128 + lane], i1 = IDS[(size_t)tok * 128 + 64 + lane];
;       const u32x4 hq = *(const u32x4*)(H2Q + (size_t)tok * D_ + s * 256 + l15 * 16);
;       wave_lds_sync();
;       lw[(lane & 3) * 32 + (lane >> 2)] = i0;
;       lw[(lane & 3) * 32 + 16 + (lane >> 2)] = i1;
;       wave_lds_sync();
;       const unsigned char* ub = U8 + s * 256 + l15 * 16;
; #pragma unroll
;       for (int batch = 0; batch < 2; ++batch) {
;         int ida[16];
; #pragma unroll
;         for (int q = 0; q < 4; ++q) { const int4 v = *(const int4*)(lw + g * 32 + batch * 16 + q * 4); ida[q * 4] = v.x; ida[q * 4 + 1] = v.y; ida[q * 4 + 2] = v.z; ida[q * 4 + 3] = v.w; }
;         u32x4 rows[16];
; #pragma unroll
;         for (int k = 0; k < 16; ++k) rows[k] = *(const u32x4*)(ub + (size_t)ida[k] * 2048);
;         int part[16];
; #pragma unroll
;         for (int k = 0; k < 16; ++k) {
;           int acc = 0;
; #pragma unroll
;           for (int d = 0; d < 4; ++d) acc = __builtin_amdgcn_sdot4((int)rows[k][d], (int)hq[d], acc, false);
.Lp9_body:
	s_add_i32 s36, s34, 0
	s_lshl_b32 s46, s36, 9
	s_add_i32 s46, s46, s24
	s_add_i32 s37, s34, 1
	s_lshl_b32 s47, s37, 9
	s_add_u32 s42, s6, s47
	s_addc_u32 s43, s7, 0
	s_lshl_b32 s47, s37, 11
	s_add_u32 s44, s22, s47
	s_addc_u32 s45, s23, 0
	global_load_dword v10, v3, s[42:43]
	global_load_dword v11, v3, s[42:43] offset:256
	global_load_dwordx4 v[16:19], v2, s[44:45]
	s_waitcnt lgkmcnt(0)
	v_lshl_add_u32 v20, v20, 11, v2
	v_lshl_add_u32 v21, v21, 11, v2
	v_lshl_add_u32 v22, v22, 11, v2
	v_lshl_add_u32 v23, v23, 11, v2
	v_lshl_add_u32 v24, v24, 11, v2
	v_lshl_add_u32 v25, v25, 11, v2
	v_lshl_add_u32 v26, v26, 11, v2
	v_lshl_add_u32 v27, v27, 11, v2
	v_lshl_add_u32 v28, v28, 11, v2
	v_lshl_add_u32 v29, v29, 11, v2
	v_lshl_add_u32 v30, v30, 11, v2
	v_lshl_add_u32 v31, v31, 11, v2
	v_lshl_add_u32 v32, v32, 11, v2
	v_lshl_add_u32 v33, v33, 11, v2
	v_lshl_add_u32 v34, v34, 11, v2
	v_lshl_add_u32 v35, v35, 11, v2
	v_lshl_add_u32 v36, v36, 11, v2
	v_lshl_add_u32 v37, v37, 11, v2
	v_lshl_add_u32 v38, v38, 11, v2
	v_lshl_add_u32 v39, v39, 11, v2
	v_lshl_add_u32 v40, v40, 11, v2
	v_lshl_add_u32 v41, v41, 11, v2
	v_lshl_add_u32 v42, v42, 11, v2
	v_lshl_add_u32 v43, v43, 11, v2
	v_lshl_add_u32 v44, v44, 11, v2
	v_lshl_add_u32 v45, v45, 11, v2
	v_lshl_add_u32 v46, v46, 11, v2
	v_lshl_add_u32 v47, v47, 11, v2
	v_lshl_add_u32 v48, v48, 11, v2
	v_lshl_add_u32 v49, v49, 11, v2
	v_lshl_add_u32 v50, v50, 11, v2
	v_lshl_add_u32 v51, v51, 11, v2
	global_load_dwordx4 v[84:87], v20, s[20:21]
	global_load_dwordx4 v[88:91], v21, s[20:21]
	global_load_dwordx4 v[92:95], v22, s[20:21]
	global_load_dwordx4 v[96:99], v23, s[20:21]
	global_load_dwordx4 v[100:103], v24, s[20:21]
	global_load_dwordx4 v[104:107], v25, s[20:21]
	global_load_dwordx4 v[108:111], v26, s[20:21]
	global_load_dwordx4 v[112:115], v27, s[20:21]
	global_load_dwordx4 v[116:119], v28, s[20:21]
	global_load_dwordx4 v[120:123], v29, s[20:21]
	global_load_dwordx4 v[124:127], v30, s[20:21]
	global_load_dwordx4 v[128:131], v31, s[20:21]
	global_load_dwordx4 v[132:135], v32, s[20:21]
	global_load_dwordx4 v[136:139], v33, s[20:21]
	global_load_dwordx4 v[140:143], v34, s[20:21]
	global_load_dwordx4 v[144:147], v35, s[20:21]
	global_load_dwordx4 v[148:151], v36, s[20:21]
	global_load_dwordx4 v[152:155], v37, s[20:21]
	global_load_dwordx4 v[156:159], v38, s[20:21]
	global_load_dwordx4 v[160:163], v39, s[20:21]
	global_load_dwordx4 v[164:167], v40, s[20:21]
	global_load_dwordx4 v[168:171], v41, s[20:21]
	global_load_dwordx4 v[172:175], v42, s[20:21]
	global_load_dwordx4 v[176:179], v43, s[20:21]
	global_load_dwordx4 v[180:183], v44, s[20:21]
	global_load_dwordx4 v[184:187], v45, s[20:21]
	global_load_dwordx4 v[190:193], v46, s[20:21]
	global_load_dwordx4 v[194:197], v47, s[20:21]
	global_load_dwordx4 v[198:201], v48, s[20:21]
	global_load_dwordx4 v[202:205], v49, s[20:21]
	global_load_dwordx4 v[206:209], v50, s[20:21]
	global_load_dwordx4 v[210:213], v51, s[20:21]
	v_mov_b32_e32 v52, 0
	v_mov_b32_e32 v53, 0
	v_mov_b32_e32 v54, 0
	v_mov_b32_e32 v55, 0
	v_mov_b32_e32 v56, 0
	v_mov_b32_e32 v57, 0
	v_mov_b32_e32 v58, 0
	v_mov_b32_e32 v59, 0
	v_mov_b32_e32 v60, 0
	v_mov_b32_e32 v61, 0
	v_mov_b32_e32 v62, 0
	v_mov_b32_e32 v63, 0
	v_mov_b32_e32 v64, 0
	v_mov_b32_e32 v65, 0
	v_mov_b32_e32 v66, 0
	v_mov_b32_e32 v67, 0
	v_mov_b32_e32 v68, 0
	v_mov_b32_e32 v69, 0
	v_mov_b32_e32 v70, 0
	v_mov_b32_e32 v71, 0
	v_mov_b32_e32 v72, 0
	v_mov_b32_e32 v73, 0
	v_mov_b32_e32 v74, 0
	v_mov_b32_e32 v75, 0
	v_mov_b32_e32 v76, 0
	v_mov_b32_e32 v77, 0
	v_mov_b32_e32 v78, 0
	v_mov_b32_e32 v79, 0
	v_mov_b32_e32 v80, 0
	v_mov_b32_e32 v81, 0
	v_mov_b32_e32 v82, 0
	v_mov_b32_e32 v83, 0
	s_waitcnt vmcnt(31)
	v_dot4c_i32_i8_e32 v52, v84, v12
	s_waitcnt vmcnt(30)
	v_dot4c_i32_i8_e32 v53, v88, v12
	s_waitcnt vmcnt(29)
	v_dot4c_i32_i8_e32 v54, v92, v12
	s_waitcnt vmcnt(28)
	v_dot4c_i32_i8_e32 v55, v96, v12
	s_waitcnt vmcnt(27)
	v_dot4c_i32_i8_e32 v56, v100, v12
	s_waitcnt vmcnt(26)
	v_dot4c_i32_i8_e32 v57, v104, v12
	s_waitcnt vmcnt(25)
	v_dot4c_i32_i8_e32 v58, v108, v12
	s_waitcnt vmcnt(24)
	v_dot4c_i32_i8_e32 v59, v112, v12
	s_waitcnt vmcnt(23)
	v_dot4c_i32_i8_e32 v60, v116, v12
	s_waitcnt vmcnt(22)
	v_dot4c_i32_i8_e32 v61, v120, v12
	s_waitcnt vmcnt(21)
	v_dot4c_i32_i8_e32 v62, v124, v12
	s_waitcnt vmcnt(20)
	v_dot4c_i32_i8_e32 v63, v128, v12
	s_waitcnt vmcnt(19)
	v_dot4c_i32_i8_e32 v64, v132, v12
	s_waitcnt vmcnt(18)
	v_dot4c_i32_i8_e32 v65, v136, v12
	s_waitcnt vmcnt(17)
	v_dot4c_i32_i8_e32 v66, v140, v12
	s_waitcnt vmcnt(16)
	v_dot4c_i32_i8_e32 v67, v144, v12
	v_dot4c_i32_i8_e32 v52, v85, v13
	v_dot4c_i32_i8_e32 v53, v89, v13
	v_dot4c_i32_i8_e32 v54, v93, v13
	v_dot4c_i32_i8_e32 v55, v97, v13
	v_dot4c_i32_i8_e32 v56, v101, v13
	v_dot4c_i32_i8_e32 v57, v105, v13
	v_dot4c_i32_i8_e32 v58, v109, v13
	v_dot4c_i32_i8_e32 v59, v113, v13
	v_dot4c_i32_i8_e32 v60, v117, v13
	v_dot4c_i32_i8_e32 v61, v121, v13
	v_dot4c_i32_i8_e32 v62, v125, v13
	v_dot4c_i32_i8_e32 v63, v129, v13
	v_dot4c_i32_i8_e32 v64, v133, v13
	v_dot4c_i32_i8_e32 v65, v137, v13
	v_dot4c_i32_i8_e32 v66, v141, v13
	v_dot4c_i32_i8_e32 v67, v145, v13
	v_dot4c_i32_i8_e32 v52, v86, v14
	v_dot4c_i32_i8_e32 v53, v90, v14
	v_dot4c_i32_i8_e32 v54, v94, v14
	v_dot4c_i32_i8_e32 v55, v98, v14
	v_dot4c_i32_i8_e32 v56, v102, v14
	v_dot4c_i32_i8_e32 v57, v106, v14
	v_dot4c_i32_i8_e32 v58, v110, v14
	v_dot4c_i32_i8_e32 v59, v114, v14
	v_dot4c_i32_i8_e32 v60, v118, v14
	v_dot4c_i32_i8_e32 v61, v122, v14
	v_dot4c_i32_i8_e32 v62, v126, v14
	v_dot4c_i32_i8_e32 v63, v130, v14
	v_dot4c_i32_i8_e32 v64, v134, v14
	v_dot4c_i32_i8_e32 v65, v138, v14
	v_dot4c_i32_i8_e32 v66, v142, v14
	v_dot4c_i32_i8_e32 v67, v146, v14
	v_dot4c_i32_i8_e32 v52, v87, v15
	v_dot4c_i32_i8_e32 v53, v91, v15
	v_dot4c_i32_i8_e32 v54, v95, v15
	v_dot4c_i32_i8_e32 v55, v99, v15
	v_dot4c_i32_i8_e32 v56, v103, v15
	v_dot4c_i32_i8_e32 v57, v107, v15
	v_dot4c_i32_i8_e32 v58, v111, v15
	v_dot4c_i32_i8_e32 v59, v115, v15
	v_dot4c_i32_i8_e32 v60, v119, v15
	v_dot4c_i32_i8_e32 v61, v123, v15
	v_dot4c_i32_i8_e32 v62, v127, v15
	v_dot4c_i32_i8_e32 v63, v131, v15
	v_dot4c_i32_i8_e32 v64, v135, v15
	v_dot4c_i32_i8_e32 v65, v139, v15
	v_dot4c_i32_i8_e32 v66, v143, v15
	v_dot4c_i32_i8_e32 v67, v147, v15
	ds_write2_b32 v5, v10, v11 offset0:4 offset1:20
	s_waitcnt lgkmcnt(0)
; DI void phase9(const Params& p, char* smem, int rep) {
;     ...
;         for (int q = 0; q < 4; ++q) { const int4 v = *(const int4*)(lw + g * 32 + batch * 16 + q * 4); ida[q * 4] = v.x; ida[q * 4 + 1] = v.y; ida[q * 4 + 2] = v.z; ida[q * 4 + 3] = v.w; }
;         u32x4 rows[16];
; #pragma unroll
;         for (int k = 0; k < 16; ++k) rows[k] = *(const u32x4*)(ub + (size_t)ida[k] * 2048);
;         int part[16];
; #pragma unroll
;         for (int k = 0; k < 16; ++k) {
;           int acc = 0;
; #pragma unroll
;           for (int d = 0; d < 4; ++d) acc = __builtin_amdgcn_sdot4((int)rows[k][d], (int)hq[d], acc, false);
;           part[k] = acc;
;         }
;         int q8[8], q4[4], q2[2];
; #pragma unroll
;         for (int k = 0; k < 8; ++k) q8[k] = (b3 ? part[8 + k] : part[k]) + __shfl_xor(b3 ? part[k] : part[8 + k], 8);
; #pragma unroll
;         for (int k = 0; k < 4; ++k) q4[k] = (b2 ? q8[4 + k] : q8[k]) + __shfl_xor(b2 ? q8[k] : q8[4 + k], 4);
; #pragma unroll
;         for (int k = 0; k < 2; ++k) q2[k] = (b1 ? q4[2 + k] : q4[k]) + __shfl_xor(b1 ? q4[k] : q4[2 + k], 2);
;         const int rr = (b0 ? q2[1] : q2[0]) + __shfl_xor(b0 ? q2[0] : q2[1], 1);
;         PA[((size_t)s * T_ + tok) * 128 + 4 * (batch * 16 + l15) + g] = rr;
	ds_read_b128 v[20:23], v6 offset:16
	ds_read_b128 v[24:27], v6 offset:32
	ds_read_b128 v[28:31], v6 offset:48
	ds_read_b128 v[32:35], v6 offset:64
	ds_read_b128 v[36:39], v6 offset:80
	ds_read_b128 v[40:43], v6 offset:96
	ds_read_b128 v[44:47], v6 offset:112
	ds_read_b128 v[48:51], v6 offset:128
	v_add_u32_dpp v84, v52, v52 row_ror:8 row_mask:0xf bank_mask:0x3
	v_add_u32_dpp v84, v60, v60 row_ror:8 row_mask:0xf bank_mask:0xc
	v_add_u32_dpp v85, v53, v53 row_ror:8 row_mask:0xf bank_mask:0x3
	v_add_u32_dpp v85, v61, v61 row_ror:8 row_mask:0xf bank_mask:0xc
	v_add_u32_dpp v86, v54, v54 row_ror:8 row_mask:0xf bank_mask:0x3
	v_add_u32_dpp v86, v62, v62 row_ror:8 row_mask:0xf bank_mask:0xc
	v_add_u32_dpp v87, v55, v55 row_ror:8 row_mask:0xf bank_mask:0x3
	v_add_u32_dpp v87, v63, v63 row_ror:8 row_mask:0xf bank_mask:0xc
	v_add_u32_dpp v88, v56, v56 row_ror:8 row_mask:0xf bank_mask:0x3
	v_add_u32_dpp v88, v64, v64 row_ror:8 row_mask:0xf bank_mask:0xc
	v_add_u32_dpp v89, v57, v57 row_ror:8 row_mask:0xf bank_mask:0x3
	v_add_u32_dpp v89, v65, v65 row_ror:8 row_mask:0xf bank_mask:0xc
	v_add_u32_dpp v90, v58, v58 row_ror:8 row_mask:0xf bank_mask:0x3
	v_add_u32_dpp v90, v66, v66 row_ror:8 row_mask:0xf bank_mask:0xc
	v_add_u32_dpp v91, v59, v59 row_ror:8 row_mask:0xf bank_mask:0x3
	v_add_u32_dpp v91, v67, v67 row_ror:8 row_mask:0xf bank_mask:0xc
	v_add_u32_dpp v92, v84, v84 row_half_mirror row_mask:0xf bank_mask:0x5
	v_add_u32_dpp v92, v88, v88 row_half_mirror row_mask:0xf bank_mask:0xa
	v_add_u32_dpp v93, v85, v85 row_half_mirror row_mask:0xf bank_mask:0x5
	v_add_u32_dpp v93, v89, v89 row_half_mirror row_mask:0xf bank_mask:0xa
	v_add_u32_dpp v94, v86, v86 row_half_mirror row_mask:0xf bank_mask:0x5
	v_add_u32_dpp v94, v90, v90 row_half_mirror row_mask:0xf bank_mask:0xa
	v_add_u32_dpp v95, v87, v87 row_half_mirror row_mask:0xf bank_mask:0x5
	v_add_u32_dpp v95, v91, v91 row_half_mirror row_mask:0xf bank_mask:0xa
	v_add_u32_dpp v96, v92, v92 quad_perm:[2,3,0,1] row_mask:0xf bank_mask:0xf
	v_add_u32_dpp v97, v93, v93 quad_perm:[2,3,0,1] row_mask:0xf bank_mask:0xf
	v_add_u32_dpp v98, v94, v94 quad_perm:[2,3,0,1] row_mask:0xf bank_mask:0xf
	s_nop 0
	v_add_u32_dpp v99, v95, v95 quad_perm:[2,3,0,1] row_mask:0xf bank_mask:0xf
	v_cndmask_b32_e64 v100, v98, v96, s[2:3]
	v_cndmask_b32_e64 v101, v99, v97, s[2:3]
	v_add_u32_e32 v214, s46, v4
	s_nop 1
	v_add_u32_dpp v102, v100, v100 quad_perm:[1,0,3,2] row_mask:0xf bank_mask:0xf
	v_add_u32_dpp v103, v101, v101 quad_perm:[1,0,3,2] row_mask:0xf bank_mask:0xf
	v_cndmask_b32_e64 v104, v103, v102, s[4:5]
	global_store_dword v214, v104, s[14:15]
	s_waitcnt vmcnt(16)
	v_dot4c_i32_i8_e32 v68, v148, v12
	s_waitcnt vmcnt(15)
	v_dot4c_i32_i8_e32 v69, v152, v12
	s_waitcnt vmcnt(14)
	v_dot4c_i32_i8_e32 v70, v156, v12
	s_waitcnt vmcnt(13)
	v_dot4c_i32_i8_e32 v71, v160, v12
	s_waitcnt vmcnt(12)
	v_dot4c_i32_i8_e32 v72, v164, v12
	s_waitcnt vmcnt(11)
	v_dot4c_i32_i8_e32 v73, v168, v12
	s_waitcnt vmcnt(10)
	v_dot4c_i32_i8_e32 v74, v172, v12
	s_waitcnt vmcnt(9)
	v_dot4c_i32_i8_e32 v75, v176, v12
	s_waitcnt vmcnt(8)
	v_dot4c_i32_i8_e32 v76, v180, v12
	s_waitcnt vmcnt(7)
	v_dot4c_i32_i8_e32 v77, v184, v12
	s_waitcnt vmcnt(6)
	v_dot4c_i32_i8_e32 v78, v190, v12
	s_waitcnt vmcnt(5)
	v_dot4c_i32_i8_e32 v79, v194, v12
	s_waitcnt vmcnt(4)
	v_dot4c_i32_i8_e32 v80, v198, v12
	s_waitcnt vmcnt(3)
	v_dot4c_i32_i8_e32 v81, v202, v12
	s_waitcnt vmcnt(2)
	v_dot4c_i32_i8_e32 v82, v206, v12
	s_waitcnt vmcnt(1)
	v_dot4c_i32_i8_e32 v83, v210, v12
	v_dot4c_i32_i8_e32 v68, v149, v13
	v_dot4c_i32_i8_e32 v69, v153, v13
	v_dot4c_i32_i8_e32 v70, v157, v13
	v_dot4c_i32_i8_e32 v71, v161, v13
	v_dot4c_i32_i8_e32 v72, v165, v13
	v_dot4c_i32_i8_e32 v73, v169, v13
	v_dot4c_i32_i8_e32 v74, v173, v13
	v_dot4c_i32_i8_e32 v75, v177, v13
	v_dot4c_i32_i8_e32 v76, v181, v13
	v_dot4c_i32_i8_e32 v77, v185, v13
	v_dot4c_i32_i8_e32 v78, v191, v13
	v_dot4c_i32_i8_e32 v79, v195, v13
	v_dot4c_i32_i8_e32 v80, v199, v13
	v_dot4c_i32_i8_e32 v81, v203, v13
	v_dot4c_i32_i8_e32 v82, v207, v13
	v_dot4c_i32_i8_e32 v83, v211, v13
	v_dot4c_i32_i8_e32 v68, v150, v14
	v_dot4c_i32_i8_e32 v69, v154, v14
	v_dot4c_i32_i8_e32 v70, v158, v14
	v_dot4c_i32_i8_e32 v71, v162, v14
	v_dot4c_i32_i8_e32 v72, v166, v14
	v_dot4c_i32_i8_e32 v73, v170, v14
	v_dot4c_i32_i8_e32 v74, v174, v14
	v_dot4c_i32_i8_e32 v75, v178, v14
	v_dot4c_i32_i8_e32 v76, v182, v14
	v_dot4c_i32_i8_e32 v77, v186, v14
	v_dot4c_i32_i8_e32 v78, v192, v14
	v_dot4c_i32_i8_e32 v79, v196, v14
	v_dot4c_i32_i8_e32 v80, v200, v14
	v_dot4c_i32_i8_e32 v81, v204, v14
	v_dot4c_i32_i8_e32 v82, v208, v14
	v_dot4c_i32_i8_e32 v83, v212, v14
	v_dot4c_i32_i8_e32 v68, v151, v15
	v_dot4c_i32_i8_e32 v69, v155, v15
	v_dot4c_i32_i8_e32 v70, v159, v15
	v_dot4c_i32_i8_e32 v71, v163, v15
	v_dot4c_i32_i8_e32 v72, v167, v15
	v_dot4c_i32_i8_e32 v73, v171, v15
	v_dot4c_i32_i8_e32 v74, v175, v15
	v_dot4c_i32_i8_e32 v75, v179, v15
	v_dot4c_i32_i8_e32 v76, v183, v15
	v_dot4c_i32_i8_e32 v77, v187, v15
	v_dot4c_i32_i8_e32 v78, v193, v15
	v_dot4c_i32_i8_e32 v79, v197, v15
	v_dot4c_i32_i8_e32 v80, v201, v15
	v_dot4c_i32_i8_e32 v81, v205, v15
	v_dot4c_i32_i8_e32 v82, v209, v15
	v_dot4c_i32_i8_e32 v83, v213, v15
	v_add_u32_dpp v148, v68, v68 row_ror:8 row_mask:0xf bank_mask:0x3
	v_add_u32_dpp v148, v76, v76 row_ror:8 row_mask:0xf bank_mask:0xc
	v_add_u32_dpp v149, v69, v69 row_ror:8 row_mask:0xf bank_mask:0x3
	v_add_u32_dpp v149, v77, v77 row_ror:8 row_mask:0xf bank_mask:0xc
	v_add_u32_dpp v150, v70, v70 row_ror:8 row_mask:0xf bank_mask:0x3
	v_add_u32_dpp v150, v78, v78 row_ror:8 row_mask:0xf bank_mask:0xc
	v_add_u32_dpp v151, v71, v71 row_ror:8 row_mask:0xf bank_mask:0x3
; DI void wave_lds_sync() { asm volatile("s_waitcnt lgkmcnt(0)" ::: "memory"); __builtin_amdgcn_wave_barrier(); }
; DI void phase9(const Params& p, char* smem, int rep) {
;     ...
;       const int tok = __builtin_amdgcn_readfirstlane(c * 16 + w * 4 + t);
;       const int i0 = IDS[(size_t)tok * 128 + lane], i1 = IDS[(size_t)tok * 128 + 64 + lane];
;       const u32x4 hq = *(const u32x4*)(H2Q + (size_t)tok * D_ + s * 256 + l15 * 16);
;       wave_lds_sync();
;       lw[(lane & 3) * 32 + (lane >> 2)] = i0;
;       lw[(lane & 3) * 32 + 16 + (lane >> 2)] = i1;
;       wave_lds_sync();
;       const unsigned char* ub = U8 + s * 256 + l15 * 16;
; #pragma unroll
;       for (int batch = 0; batch < 2; ++batch) {
;         int ida[16];
; #pragma unroll
;         for (int q = 0; q < 4; ++q) { const int4 v = *(const int4*)(lw + g * 32 + batch * 16 + q * 4); ida[q * 4] = v.x; ida[q * 4 + 1] = v.y; ida[q * 4 + 2] = v.z; ida[q * 4 + 3] = v.w; }
;         u32x4 rows[16];
; #pragma unroll
;         for (int k = 0; k < 16; ++k) rows[k] = *(const u32x4*)(ub + (size_t)ida[k] * 2048);
;         int part[16];
; #pragma unroll
;         for (int k = 0; k < 16; ++k) {
;           int acc = 0;
; #pragma unroll
;           for (int d = 0; d < 4; ++d) acc = __builtin_amdgcn_sdot4((int)rows[k][d], (int)hq[d], acc, false);
;     ...
;         int q8[8], q4[4], q2[2];
; #pragma unroll
;         for (int k = 0; k < 8; ++k) q8[k] = (b3 ? part[8 + k] : part[k]) + __shfl_xor(b3 ? part[k] : part[8 + k], 8);
; #pragma unroll
;         for (int k = 0; k < 4; ++k) q4[k] = (b2 ? q8[4 + k] : q8[k]) + __shfl_xor(b2 ? q8[k] : q8[4 + k], 4);
; #pragma unroll
;         for (int k = 0; k < 2; ++k) q2[k] = (b1 ? q4[2 + k] : q4[k]) + __shfl_xor(b1 ? q4[k] : q4[2 + k], 2);
;         const int rr = (b0 ? q2[1] : q2[0]) + __shfl_xor(b0 ? q2[0] : q2[1], 1);
;         PA[((size_t)s * T_ + tok) * 128 + 4 * (batch * 16 + l15) + g] = rr;
	v_add_u32_dpp v151, v79, v79 row_ror:8 row_mask:0xf bank_mask:0xc
	v_add_u32_dpp v152, v72, v72 row_ror:8 row_mask:0xf bank_mask:0x3
	v_add_u32_dpp v152, v80, v80 row_ror:8 row_mask:0xf bank_mask:0xc
	v_add_u32_dpp v153, v73, v73 row_ror:8 row_mask:0xf bank_mask:0x3
	v_add_u32_dpp v153, v81, v81 row_ror:8 row_mask:0xf bank_mask:0xc
	v_add_u32_dpp v154, v74, v74 row_ror:8 row_mask:0xf bank_mask:0x3
	v_add_u32_dpp v154, v82, v82 row_ror:8 row_mask:0xf bank_mask:0xc
	v_add_u32_dpp v155, v75, v75 row_ror:8 row_mask:0xf bank_mask:0x3
	v_add_u32_dpp v155, v83, v83 row_ror:8 row_mask:0xf bank_mask:0xc
	v_add_u32_dpp v156, v148, v148 row_half_mirror row_mask:0xf bank_mask:0x5
	v_add_u32_dpp v156, v152, v152 row_half_mirror row_mask:0xf bank_mask:0xa
	v_add_u32_dpp v157, v149, v149 row_half_mirror row_mask:0xf bank_mask:0x5
	v_add_u32_dpp v157, v153, v153 row_half_mirror row_mask:0xf bank_mask:0xa
	v_add_u32_dpp v158, v150, v150 row_half_mirror row_mask:0xf bank_mask:0x5
	v_add_u32_dpp v158, v154, v154 row_half_mirror row_mask:0xf bank_mask:0xa
	v_add_u32_dpp v159, v151, v151 row_half_mirror row_mask:0xf bank_mask:0x5
	v_add_u32_dpp v159, v155, v155 row_half_mirror row_mask:0xf bank_mask:0xa
	v_add_u32_dpp v160, v156, v156 quad_perm:[2,3,0,1] row_mask:0xf bank_mask:0xf
	v_add_u32_dpp v161, v157, v157 quad_perm:[2,3,0,1] row_mask:0xf bank_mask:0xf
	v_add_u32_dpp v162, v158, v158 quad_perm:[2,3,0,1] row_mask:0xf bank_mask:0xf
	s_nop 0
	v_add_u32_dpp v163, v159, v159 quad_perm:[2,3,0,1] row_mask:0xf bank_mask:0xf
	v_cndmask_b32_e64 v164, v162, v160, s[2:3]
	v_cndmask_b32_e64 v165, v163, v161, s[2:3]
	s_nop 0
	s_nop 1
	v_add_u32_dpp v166, v164, v164 quad_perm:[1,0,3,2] row_mask:0xf bank_mask:0xf
	v_add_u32_dpp v167, v165, v165 quad_perm:[1,0,3,2] row_mask:0xf bank_mask:0xf
	v_cndmask_b32_e64 v168, v167, v166, s[4:5]
	global_store_dword v214, v168, s[14:15] offset:256 nt
	s_add_i32 s36, s34, 1
	s_lshl_b32 s46, s36, 9
	s_add_i32 s46, s46, s24
	s_add_i32 s37, s34, 2
	s_lshl_b32 s47, s37, 9
	s_add_u32 s42, s6, s47
	s_addc_u32 s43, s7, 0
	s_lshl_b32 s47, s37, 11
	s_add_u32 s44, s22, s47
	s_addc_u32 s45, s23, 0
	global_load_dword v10, v3, s[42:43]
	global_load_dword v11, v3, s[42:43] offset:256
	global_load_dwordx4 v[12:15], v2, s[44:45]
	s_waitcnt lgkmcnt(0)
	v_lshl_add_u32 v20, v20, 11, v2
	v_lshl_add_u32 v21, v21, 11, v2
	v_lshl_add_u32 v22, v22, 11, v2
	v_lshl_add_u32 v23, v23, 11, v2
	v_lshl_add_u32 v24, v24, 11, v2
	v_lshl_add_u32 v25, v25, 11, v2
	v_lshl_add_u32 v26, v26, 11, v2
	v_lshl_add_u32 v27, v27, 11, v2
	v_lshl_add_u32 v28, v28, 11, v2
	v_lshl_add_u32 v29, v29, 11, v2
	v_lshl_add_u32 v30, v30, 11, v2
	v_lshl_add_u32 v31, v31, 11, v2
	v_lshl_add_u32 v32, v32, 11, v2
	v_lshl_add_u32 v33, v33, 11, v2
	v_lshl_add_u32 v34, v34, 11, v2
	v_lshl_add_u32 v35, v35, 11, v2
	v_lshl_add_u32 v36, v36, 11, v2
	v_lshl_add_u32 v37, v37, 11, v2
	v_lshl_add_u32 v38, v38, 11, v2
	v_lshl_add_u32 v39, v39, 11, v2
	v_lshl_add_u32 v40, v40, 11, v2
	v_lshl_add_u32 v41, v41, 11, v2
	v_lshl_add_u32 v42, v42, 11, v2
	v_lshl_add_u32 v43, v43, 11, v2
	v_lshl_add_u32 v44, v44, 11, v2
	v_lshl_add_u32 v45, v45, 11, v2
	v_lshl_add_u32 v46, v46, 11, v2
	v_lshl_add_u32 v47, v47, 11, v2
	v_lshl_add_u32 v48, v48, 11, v2
	v_lshl_add_u32 v49, v49, 11, v2
	v_lshl_add_u32 v50, v50, 11, v2
	v_lshl_add_u32 v51, v51, 11, v2
	global_load_dwordx4 v[84:87], v20, s[20:21]
	global_load_dwordx4 v[88:91], v21, s[20:21]
	global_load_dwordx4 v[92:95], v22, s[20:21]
	global_load_dwordx4 v[96:99], v23, s[20:21]
	global_load_dwordx4 v[100:103], v24, s[20:21]
	global_load_dwordx4 v[104:107], v25, s[20:21]
	global_load_dwordx4 v[108:111], v26, s[20:21]
	global_load_dwordx4 v[112:115], v27, s[20:21]
	global_load_dwordx4 v[116:119], v28, s[20:21]
	global_load_dwordx4 v[120:123], v29, s[20:21]
	global_load_dwordx4 v[124:127], v30, s[20:21]
	global_load_dwordx4 v[128:131], v31, s[20:21]
	global_load_dwordx4 v[132:135], v32, s[20:21]
	global_load_dwordx4 v[136:139], v33, s[20:21]
	global_load_dwordx4 v[140:143], v34, s[20:21]
	global_load_dwordx4 v[144:147], v35, s[20:21]
	global_load_dwordx4 v[148:151], v36, s[20:21]
	global_load_dwordx4 v[152:155], v37, s[20:21]
	global_load_dwordx4 v[156:159], v38, s[20:21]
	global_load_dwordx4 v[160:163], v39, s[20:21]
	global_load_dwordx4 v[164:167], v40, s[20:21]
	global_load_dwordx4 v[168:171], v41, s[20:21]
	global_load_dwordx4 v[172:175], v42, s[20:21]
	global_load_dwordx4 v[176:179], v43, s[20:21]
	global_load_dwordx4 v[180:183], v44, s[20:21]
	global_load_dwordx4 v[184:187], v45, s[20:21]
	global_load_dwordx4 v[190:193], v46, s[20:21]
	global_load_dwordx4 v[194:197], v47, s[20:21]
	global_load_dwordx4 v[198:201], v48, s[20:21]
	global_load_dwordx4 v[202:205], v49, s[20:21]
	global_load_dwordx4 v[206:209], v50, s[20:21]
	global_load_dwordx4 v[210:213], v51, s[20:21]
	v_mov_b32_e32 v52, 0
	v_mov_b32_e32 v53, 0
	v_mov_b32_e32 v54, 0
	v_mov_b32_e32 v55, 0
	v_mov_b32_e32 v56, 0
	v_mov_b32_e32 v57, 0
	v_mov_b32_e32 v58, 0
	v_mov_b32_e32 v59, 0
	v_mov_b32_e32 v60, 0
	v_mov_b32_e32 v61, 0
	v_mov_b32_e32 v62, 0
	v_mov_b32_e32 v63, 0
	v_mov_b32_e32 v64, 0
	v_mov_b32_e32 v65, 0
	v_mov_b32_e32 v66, 0
	v_mov_b32_e32 v67, 0
	v_mov_b32_e32 v68, 0
	v_mov_b32_e32 v69, 0
	v_mov_b32_e32 v70, 0
	v_mov_b32_e32 v71, 0
	v_mov_b32_e32 v72, 0
	v_mov_b32_e32 v73, 0
	v_mov_b32_e32 v74, 0
	v_mov_b32_e32 v75, 0
	v_mov_b32_e32 v76, 0
	v_mov_b32_e32 v77, 0
	v_mov_b32_e32 v78, 0
	v_mov_b32_e32 v79, 0
	v_mov_b32_e32 v80, 0
	v_mov_b32_e32 v81, 0
	v_mov_b32_e32 v82, 0
	v_mov_b32_e32 v83, 0
	s_waitcnt vmcnt(31)
	v_dot4c_i32_i8_e32 v52, v84, v16
	s_waitcnt vmcnt(30)
; DI void phase9(const Params& p, char* smem, int rep) {
;     ...
;         for (int q = 0; q < 4; ++q) { const int4 v = *(const int4*)(lw + g * 32 + batch * 16 + q * 4); ida[q * 4] = v.x; ida[q * 4 + 1] = v.y; ida[q * 4 + 2] = v.z; ida[q * 4 + 3] = v.w; }
;         u32x4 rows[16];
; #pragma unroll
;         for (int k = 0; k < 16; ++k) rows[k] = *(const u32x4*)(ub + (size_t)ida[k] * 2048);
;         int part[16];
; #pragma unroll
;         for (int k = 0; k < 16; ++k) {
;           int acc = 0;
; #pragma unroll
;           for (int d = 0; d < 4; ++d) acc = __builtin_amdgcn_sdot4((int)rows[k][d], (int)hq[d], acc, false);
;           part[k] = acc;
;         }
;         int q8[8], q4[4], q2[2];
; #pragma unroll
;         for (int k = 0; k < 8; ++k) q8[k] = (b3 ? part[8 + k] : part[k]) + __shfl_xor(b3 ? part[k] : part[8 + k], 8);
; #pragma unroll
;         for (int k = 0; k < 4; ++k) q4[k] = (b2 ? q8[4 + k] : q8[k]) + __shfl_xor(b2 ? q8[k] : q8[4 + k], 4);
; #pragma unroll
;         for (int k = 0; k < 2; ++k) q2[k] = (b1 ? q4[2 + k] : q4[k]) + __shfl_xor(b1 ? q4[k] : q4[2 + k], 2);
;         const int rr = (b0 ? q2[1] : q2[0]) + __shfl_xor(b0 ? q2[0] : q2[1], 1);
;         PA[((size_t)s * T_ + tok) * 128 + 4 * (batch * 16 + l15) + g] = rr;
	v_dot4c_i32_i8_e32 v53, v88, v16
	s_waitcnt vmcnt(29)
	v_dot4c_i32_i8_e32 v54, v92, v16
	s_waitcnt vmcnt(28)
	v_dot4c_i32_i8_e32 v55, v96, v16
	s_waitcnt vmcnt(27)
	v_dot4c_i32_i8_e32 v56, v100, v16
	s_waitcnt vmcnt(26)
	v_dot4c_i32_i8_e32 v57, v104, v16
	s_waitcnt vmcnt(25)
	v_dot4c_i32_i8_e32 v58, v108, v16
	s_waitcnt vmcnt(24)
	v_dot4c_i32_i8_e32 v59, v112, v16
	s_waitcnt vmcnt(23)
	v_dot4c_i32_i8_e32 v60, v116, v16
	s_waitcnt vmcnt(22)
	v_dot4c_i32_i8_e32 v61, v120, v16
	s_waitcnt vmcnt(21)
	v_dot4c_i32_i8_e32 v62, v124, v16
	s_waitcnt vmcnt(20)
	v_dot4c_i32_i8_e32 v63, v128, v16
	s_waitcnt vmcnt(19)
	v_dot4c_i32_i8_e32 v64, v132, v16
	s_waitcnt vmcnt(18)
	v_dot4c_i32_i8_e32 v65, v136, v16
	s_waitcnt vmcnt(17)
	v_dot4c_i32_i8_e32 v66, v140, v16
	s_waitcnt vmcnt(16)
	v_dot4c_i32_i8_e32 v67, v144, v16
	v_dot4c_i32_i8_e32 v52, v85, v17
	v_dot4c_i32_i8_e32 v53, v89, v17
	v_dot4c_i32_i8_e32 v54, v93, v17
	v_dot4c_i32_i8_e32 v55, v97, v17
	v_dot4c_i32_i8_e32 v56, v101, v17
	v_dot4c_i32_i8_e32 v57, v105, v17
	v_dot4c_i32_i8_e32 v58, v109, v17
	v_dot4c_i32_i8_e32 v59, v113, v17
	v_dot4c_i32_i8_e32 v60, v117, v17
	v_dot4c_i32_i8_e32 v61, v121, v17
	v_dot4c_i32_i8_e32 v62, v125, v17
	v_dot4c_i32_i8_e32 v63, v129, v17
	v_dot4c_i32_i8_e32 v64, v133, v17
	v_dot4c_i32_i8_e32 v65, v137, v17
	v_dot4c_i32_i8_e32 v66, v141, v17
	v_dot4c_i32_i8_e32 v67, v145, v17
	v_dot4c_i32_i8_e32 v52, v86, v18
	v_dot4c_i32_i8_e32 v53, v90, v18
	v_dot4c_i32_i8_e32 v54, v94, v18
	v_dot4c_i32_i8_e32 v55, v98, v18
	v_dot4c_i32_i8_e32 v56, v102, v18
	v_dot4c_i32_i8_e32 v57, v106, v18
	v_dot4c_i32_i8_e32 v58, v110, v18
	v_dot4c_i32_i8_e32 v59, v114, v18
	v_dot4c_i32_i8_e32 v60, v118, v18
	v_dot4c_i32_i8_e32 v61, v122, v18
	v_dot4c_i32_i8_e32 v62, v126, v18
	v_dot4c_i32_i8_e32 v63, v130, v18
	v_dot4c_i32_i8_e32 v64, v134, v18
	v_dot4c_i32_i8_e32 v65, v138, v18
	v_dot4c_i32_i8_e32 v66, v142, v18
	v_dot4c_i32_i8_e32 v67, v146, v18
	v_dot4c_i32_i8_e32 v52, v87, v19
	v_dot4c_i32_i8_e32 v53, v91, v19
	v_dot4c_i32_i8_e32 v54, v95, v19
	v_dot4c_i32_i8_e32 v55, v99, v19
	v_dot4c_i32_i8_e32 v56, v103, v19
	v_dot4c_i32_i8_e32 v57, v107, v19
	v_dot4c_i32_i8_e32 v58, v111, v19
	v_dot4c_i32_i8_e32 v59, v115, v19
	v_dot4c_i32_i8_e32 v60, v119, v19
	v_dot4c_i32_i8_e32 v61, v123, v19
	v_dot4c_i32_i8_e32 v62, v127, v19
	v_dot4c_i32_i8_e32 v63, v131, v19
	v_dot4c_i32_i8_e32 v64, v135, v19
	v_dot4c_i32_i8_e32 v65, v139, v19
	v_dot4c_i32_i8_e32 v66, v143, v19
	v_dot4c_i32_i8_e32 v67, v147, v19
	ds_write2_b32 v5, v10, v11 offset0:4 offset1:20
	s_waitcnt lgkmcnt(0)
	ds_read_b128 v[20:23], v6 offset:16
	ds_read_b128 v[24:27], v6 offset:32
	ds_read_b128 v[28:31], v6 offset:48
	ds_read_b128 v[32:35], v6 offset:64
	ds_read_b128 v[36:39], v6 offset:80
	ds_read_b128 v[40:43], v6 offset:96
	ds_read_b128 v[44:47], v6 offset:112
	ds_read_b128 v[48:51], v6 offset:128
	v_add_u32_dpp v84, v52, v52 row_ror:8 row_mask:0xf bank_mask:0x3
	v_add_u32_dpp v84, v60, v60 row_ror:8 row_mask:0xf bank_mask:0xc
	v_add_u32_dpp v85, v53, v53 row_ror:8 row_mask:0xf bank_mask:0x3
	v_add_u32_dpp v85, v61, v61 row_ror:8 row_mask:0xf bank_mask:0xc
	v_add_u32_dpp v86, v54, v54 row_ror:8 row_mask:0xf bank_mask:0x3
	v_add_u32_dpp v86, v62, v62 row_ror:8 row_mask:0xf bank_mask:0xc
	v_add_u32_dpp v87, v55, v55 row_ror:8 row_mask:0xf bank_mask:0x3
	v_add_u32_dpp v87, v63, v63 row_ror:8 row_mask:0xf bank_mask:0xc
	v_add_u32_dpp v88, v56, v56 row_ror:8 row_mask:0xf bank_mask:0x3
	v_add_u32_dpp v88, v64, v64 row_ror:8 row_mask:0xf bank_mask:0xc
	v_add_u32_dpp v89, v57, v57 row_ror:8 row_mask:0xf bank_mask:0x3
	v_add_u32_dpp v89, v65, v65 row_ror:8 row_mask:0xf bank_mask:0xc
	v_add_u32_dpp v90, v58, v58 row_ror:8 row_mask:0xf bank_mask:0x3
	v_add_u32_dpp v90, v66, v66 row_ror:8 row_mask:0xf bank_mask:0xc
	v_add_u32_dpp v91, v59, v59 row_ror:8 row_mask:0xf bank_mask:0x3
	v_add_u32_dpp v91, v67, v67 row_ror:8 row_mask:0xf bank_mask:0xc
	v_add_u32_dpp v92, v84, v84 row_half_mirror row_mask:0xf bank_mask:0x5
	v_add_u32_dpp v92, v88, v88 row_half_mirror row_mask:0xf bank_mask:0xa
	v_add_u32_dpp v93, v85, v85 row_half_mirror row_mask:0xf bank_mask:0x5
	v_add_u32_dpp v93, v89, v89 row_half_mirror row_mask:0xf bank_mask:0xa
	v_add_u32_dpp v94, v86, v86 row_half_mirror row_mask:0xf bank_mask:0x5
	v_add_u32_dpp v94, v90, v90 row_half_mirror row_mask:0xf bank_mask:0xa
	v_add_u32_dpp v95, v87, v87 row_half_mirror row_mask:0xf bank_mask:0x5
	v_add_u32_dpp v95, v91, v91 row_half_mirror row_mask:0xf bank_mask:0xa
	v_add_u32_dpp v96, v92, v92 quad_perm:[2,3,0,1] row_mask:0xf bank_mask:0xf
	v_add_u32_dpp v97, v93, v93 quad_perm:[2,3,0,1] row_mask:0xf bank_mask:0xf
	v_add_u32_dpp v98, v94, v94 quad_perm:[2,3,0,1] row_mask:0xf bank_mask:0xf
	s_nop 0
	v_add_u32_dpp v99, v95, v95 quad_perm:[2,3,0,1] row_mask:0xf bank_mask:0xf
	v_cndmask_b32_e64 v100, v98, v96, s[2:3]
	v_cndmask_b32_e64 v101, v99, v97, s[2:3]
	v_add_u32_e32 v214, s46, v4
	s_nop 1
	v_add_u32_dpp v102, v100, v100 quad_perm:[1,0,3,2] row_mask:0xf bank_mask:0xf
	v_add_u32_dpp v103, v101, v101 quad_perm:[1,0,3,2] row_mask:0xf bank_mask:0xf
	v_cndmask_b32_e64 v104, v103, v102, s[4:5]
	global_store_dword v214, v104, s[14:15]
	s_waitcnt vmcnt(16)
	v_dot4c_i32_i8_e32 v68, v148, v16
	s_waitcnt vmcnt(15)
	v_dot4c_i32_i8_e32 v69, v152, v16
	s_waitcnt vmcnt(14)
	v_dot4c_i32_i8_e32 v70, v156, v16
	s_waitcnt vmcnt(13)
	v_dot4c_i32_i8_e32 v71, v160, v16
	s_waitcnt vmcnt(12)
	v_dot4c_i32_i8_e32 v72, v164, v16
	s_waitcnt vmcnt(11)
	v_dot4c_i32_i8_e32 v73, v168, v16
	s_waitcnt vmcnt(10)
	v_dot4c_i32_i8_e32 v74, v172, v16
	s_waitcnt vmcnt(9)
	v_dot4c_i32_i8_e32 v75, v176, v16
	s_waitcnt vmcnt(8)
; DI void wave_lds_sync() { asm volatile("s_waitcnt lgkmcnt(0)" ::: "memory"); __builtin_amdgcn_wave_barrier(); }
; DI void phase9(const Params& p, char* smem, int rep) {
;     ...
;       const int tok = __builtin_amdgcn_readfirstlane(c * 16 + w * 4 + t);
;       const int i0 = IDS[(size_t)tok * 128 + lane], i1 = IDS[(size_t)tok * 128 + 64 + lane];
;       const u32x4 hq = *(const u32x4*)(H2Q + (size_t)tok * D_ + s * 256 + l15 * 16);
;       wave_lds_sync();
;       lw[(lane & 3) * 32 + (lane >> 2)] = i0;
;       lw[(lane & 3) * 32 + 16 + (lane >> 2)] = i1;
;       wave_lds_sync();
;       const unsigned char* ub = U8 + s * 256 + l15 * 16;
; #pragma unroll
;       for (int batch = 0; batch < 2; ++batch) {
;         int ida[16];
; #pragma unroll
;         for (int q = 0; q < 4; ++q) { const int4 v = *(const int4*)(lw + g * 32 + batch * 16 + q * 4); ida[q * 4] = v.x; ida[q * 4 + 1] = v.y; ida[q * 4 + 2] = v.z; ida[q * 4 + 3] = v.w; }
;         u32x4 rows[16];
; #pragma unroll
;         for (int k = 0; k < 16; ++k) rows[k] = *(const u32x4*)(ub + (size_t)ida[k] * 2048);
;         int part[16];
; #pragma unroll
;         for (int k = 0; k < 16; ++k) {
;           int acc = 0;
; #pragma unroll
;           for (int d = 0; d < 4; ++d) acc = __builtin_amdgcn_sdot4((int)rows[k][d], (int)hq[d], acc, false);
;           part[k] = acc;
;         }
;         int q8[8], q4[4], q2[2];
; #pragma unroll
;         for (int k = 0; k < 8; ++k) q8[k] = (b3 ? part[8 + k] : part[k]) + __shfl_xor(b3 ? part[k] : part[8 + k], 8);
; #pragma unroll
;         for (int k = 0; k < 4; ++k) q4[k] = (b2 ? q8[4 + k] : q8[k]) + __shfl_xor(b2 ? q8[k] : q8[4 + k], 4);
; #pragma unroll
;         for (int k = 0; k < 2; ++k) q2[k] = (b1 ? q4[2 + k] : q4[k]) + __shfl_xor(b1 ? q4[k] : q4[2 + k], 2);
;         const int rr = (b0 ? q2[1] : q2[0]) + __shfl_xor(b0 ? q2[0] : q2[1], 1);
;         PA[((size_t)s * T_ + tok) * 128 + 4 * (batch * 16 + l15) + g] = rr;
	v_dot4c_i32_i8_e32 v76, v180, v16
	s_waitcnt vmcnt(7)
	v_dot4c_i32_i8_e32 v77, v184, v16
	s_waitcnt vmcnt(6)
	v_dot4c_i32_i8_e32 v78, v190, v16
	s_waitcnt vmcnt(5)
	v_dot4c_i32_i8_e32 v79, v194, v16
	s_waitcnt vmcnt(4)
	v_dot4c_i32_i8_e32 v80, v198, v16
	s_waitcnt vmcnt(3)
	v_dot4c_i32_i8_e32 v81, v202, v16
	s_waitcnt vmcnt(2)
	v_dot4c_i32_i8_e32 v82, v206, v16
	s_waitcnt vmcnt(1)
	v_dot4c_i32_i8_e32 v83, v210, v16
	v_dot4c_i32_i8_e32 v68, v149, v17
	v_dot4c_i32_i8_e32 v69, v153, v17
	v_dot4c_i32_i8_e32 v70, v157, v17
	v_dot4c_i32_i8_e32 v71, v161, v17
	v_dot4c_i32_i8_e32 v72, v165, v17
	v_dot4c_i32_i8_e32 v73, v169, v17
	v_dot4c_i32_i8_e32 v74, v173, v17
	v_dot4c_i32_i8_e32 v75, v177, v17
	v_dot4c_i32_i8_e32 v76, v181, v17
	v_dot4c_i32_i8_e32 v77, v185, v17
	v_dot4c_i32_i8_e32 v78, v191, v17
	v_dot4c_i32_i8_e32 v79, v195, v17
	v_dot4c_i32_i8_e32 v80, v199, v17
	v_dot4c_i32_i8_e32 v81, v203, v17
	v_dot4c_i32_i8_e32 v82, v207, v17
	v_dot4c_i32_i8_e32 v83, v211, v17
	v_dot4c_i32_i8_e32 v68, v150, v18
	v_dot4c_i32_i8_e32 v69, v154, v18
	v_dot4c_i32_i8_e32 v70, v158, v18
	v_dot4c_i32_i8_e32 v71, v162, v18
	v_dot4c_i32_i8_e32 v72, v166, v18
	v_dot4c_i32_i8_e32 v73, v170, v18
	v_dot4c_i32_i8_e32 v74, v174, v18
	v_dot4c_i32_i8_e32 v75, v178, v18
	v_dot4c_i32_i8_e32 v76, v182, v18
	v_dot4c_i32_i8_e32 v77, v186, v18
	v_dot4c_i32_i8_e32 v78, v192, v18
	v_dot4c_i32_i8_e32 v79, v196, v18
	v_dot4c_i32_i8_e32 v80, v200, v18
	v_dot4c_i32_i8_e32 v81, v204, v18
	v_dot4c_i32_i8_e32 v82, v208, v18
	v_dot4c_i32_i8_e32 v83, v212, v18
	v_dot4c_i32_i8_e32 v68, v151, v19
	v_dot4c_i32_i8_e32 v69, v155, v19
	v_dot4c_i32_i8_e32 v70, v159, v19
	v_dot4c_i32_i8_e32 v71, v163, v19
	v_dot4c_i32_i8_e32 v72, v167, v19
	v_dot4c_i32_i8_e32 v73, v171, v19
	v_dot4c_i32_i8_e32 v74, v175, v19
	v_dot4c_i32_i8_e32 v75, v179, v19
	v_dot4c_i32_i8_e32 v76, v183, v19
	v_dot4c_i32_i8_e32 v77, v187, v19
	v_dot4c_i32_i8_e32 v78, v193, v19
	v_dot4c_i32_i8_e32 v79, v197, v19
	v_dot4c_i32_i8_e32 v80, v201, v19
	v_dot4c_i32_i8_e32 v81, v205, v19
	v_dot4c_i32_i8_e32 v82, v209, v19
	v_dot4c_i32_i8_e32 v83, v213, v19
	v_add_u32_dpp v148, v68, v68 row_ror:8 row_mask:0xf bank_mask:0x3
	v_add_u32_dpp v148, v76, v76 row_ror:8 row_mask:0xf bank_mask:0xc
	v_add_u32_dpp v149, v69, v69 row_ror:8 row_mask:0xf bank_mask:0x3
	v_add_u32_dpp v149, v77, v77 row_ror:8 row_mask:0xf bank_mask:0xc
	v_add_u32_dpp v150, v70, v70 row_ror:8 row_mask:0xf bank_mask:0x3
	v_add_u32_dpp v150, v78, v78 row_ror:8 row_mask:0xf bank_mask:0xc
	v_add_u32_dpp v151, v71, v71 row_ror:8 row_mask:0xf bank_mask:0x3
	v_add_u32_dpp v151, v79, v79 row_ror:8 row_mask:0xf bank_mask:0xc
	v_add_u32_dpp v152, v72, v72 row_ror:8 row_mask:0xf bank_mask:0x3
	v_add_u32_dpp v152, v80, v80 row_ror:8 row_mask:0xf bank_mask:0xc
	v_add_u32_dpp v153, v73, v73 row_ror:8 row_mask:0xf bank_mask:0x3
	v_add_u32_dpp v153, v81, v81 row_ror:8 row_mask:0xf bank_mask:0xc
	v_add_u32_dpp v154, v74, v74 row_ror:8 row_mask:0xf bank_mask:0x3
	v_add_u32_dpp v154, v82, v82 row_ror:8 row_mask:0xf bank_mask:0xc
	v_add_u32_dpp v155, v75, v75 row_ror:8 row_mask:0xf bank_mask:0x3
	v_add_u32_dpp v155, v83, v83 row_ror:8 row_mask:0xf bank_mask:0xc
	v_add_u32_dpp v156, v148, v148 row_half_mirror row_mask:0xf bank_mask:0x5
	v_add_u32_dpp v156, v152, v152 row_half_mirror row_mask:0xf bank_mask:0xa
	v_add_u32_dpp v157, v149, v149 row_half_mirror row_mask:0xf bank_mask:0x5
	v_add_u32_dpp v157, v153, v153 row_half_mirror row_mask:0xf bank_mask:0xa
	v_add_u32_dpp v158, v150, v150 row_half_mirror row_mask:0xf bank_mask:0x5
	v_add_u32_dpp v158, v154, v154 row_half_mirror row_mask:0xf bank_mask:0xa
	v_add_u32_dpp v159, v151, v151 row_half_mirror row_mask:0xf bank_mask:0x5
	v_add_u32_dpp v159, v155, v155 row_half_mirror row_mask:0xf bank_mask:0xa
	v_add_u32_dpp v160, v156, v156 quad_perm:[2,3,0,1] row_mask:0xf bank_mask:0xf
	v_add_u32_dpp v161, v157, v157 quad_perm:[2,3,0,1] row_mask:0xf bank_mask:0xf
	v_add_u32_dpp v162, v158, v158 quad_perm:[2,3,0,1] row_mask:0xf bank_mask:0xf
	s_nop 0
	v_add_u32_dpp v163, v159, v159 quad_perm:[2,3,0,1] row_mask:0xf bank_mask:0xf
	v_cndmask_b32_e64 v164, v162, v160, s[2:3]
	v_cndmask_b32_e64 v165, v163, v161, s[2:3]
	s_nop 0
	s_nop 1
	v_add_u32_dpp v166, v164, v164 quad_perm:[1,0,3,2] row_mask:0xf bank_mask:0xf
	v_add_u32_dpp v167, v165, v165 quad_perm:[1,0,3,2] row_mask:0xf bank_mask:0xf
	v_cndmask_b32_e64 v168, v167, v166, s[4:5]
	global_store_dword v214, v168, s[14:15] offset:256 nt
	s_add_i32 s36, s34, 2
	s_lshl_b32 s46, s36, 9
	s_add_i32 s46, s46, s24
	s_add_i32 s37, s34, 3
	s_lshl_b32 s47, s37, 9
	s_add_u32 s42, s6, s47
	s_addc_u32 s43, s7, 0
	s_lshl_b32 s47, s37, 11
	s_add_u32 s44, s22, s47
	s_addc_u32 s45, s23, 0
	global_load_dword v10, v3, s[42:43]
	global_load_dword v11, v3, s[42:43] offset:256
	global_load_dwordx4 v[16:19], v2, s[44:45]
	s_waitcnt lgkmcnt(0)
; DI void wave_lds_sync() { asm volatile("s_waitcnt lgkmcnt(0)" ::: "memory"); __builtin_amdgcn_wave_barrier(); }
; DI void phase9(const Params& p, char* smem, int rep) {
;     ...
;       lw[(lane & 3) * 32 + (lane >> 2)] = i0;
;       lw[(lane & 3) * 32 + 16 + (lane >> 2)] = i1;
;       wave_lds_sync();
;       const unsigned char* ub = U8 + s * 256 + l15 * 16;
; #pragma unroll
;       for (int batch = 0; batch < 2; ++batch) {
;         int ida[16];
; #pragma unroll
;         for (int q = 0; q < 4; ++q) { const int4 v = *(const int4*)(lw + g * 32 + batch * 16 + q * 4); ida[q * 4] = v.x; ida[q * 4 + 1] = v.y; ida[q * 4 + 2] = v.z; ida[q * 4 + 3] = v.w; }
;         u32x4 rows[16];
; #pragma unroll
;         for (int k = 0; k < 16; ++k) rows[k] = *(const u32x4*)(ub + (size_t)ida[k] * 2048);
;         int part[16];
; #pragma unroll
;         for (int k = 0; k < 16; ++k) {
;           int acc = 0;
; #pragma unroll
;           for (int d = 0; d < 4; ++d) acc = __builtin_amdgcn_sdot4((int)rows[k][d], (int)hq[d], acc, false);
	v_lshl_add_u32 v20, v20, 11, v2
	v_lshl_add_u32 v21, v21, 11, v2
	v_lshl_add_u32 v22, v22, 11, v2
	v_lshl_add_u32 v23, v23, 11, v2
	v_lshl_add_u32 v24, v24, 11, v2
	v_lshl_add_u32 v25, v25, 11, v2
	v_lshl_add_u32 v26, v26, 11, v2
	v_lshl_add_u32 v27, v27, 11, v2
	v_lshl_add_u32 v28, v28, 11, v2
	v_lshl_add_u32 v29, v29, 11, v2
	v_lshl_add_u32 v30, v30, 11, v2
	v_lshl_add_u32 v31, v31, 11, v2
	v_lshl_add_u32 v32, v32, 11, v2
	v_lshl_add_u32 v33, v33, 11, v2
	v_lshl_add_u32 v34, v34, 11, v2
	v_lshl_add_u32 v35, v35, 11, v2
	v_lshl_add_u32 v36, v36, 11, v2
	v_lshl_add_u32 v37, v37, 11, v2
	v_lshl_add_u32 v38, v38, 11, v2
	v_lshl_add_u32 v39, v39, 11, v2
	v_lshl_add_u32 v40, v40, 11, v2
	v_lshl_add_u32 v41, v41, 11, v2
	v_lshl_add_u32 v42, v42, 11, v2
	v_lshl_add_u32 v43, v43, 11, v2
	v_lshl_add_u32 v44, v44, 11, v2
	v_lshl_add_u32 v45, v45, 11, v2
	v_lshl_add_u32 v46, v46, 11, v2
	v_lshl_add_u32 v47, v47, 11, v2
	v_lshl_add_u32 v48, v48, 11, v2
	v_lshl_add_u32 v49, v49, 11, v2
	v_lshl_add_u32 v50, v50, 11, v2
	v_lshl_add_u32 v51, v51, 11, v2
	global_load_dwordx4 v[84:87], v20, s[20:21]
	global_load_dwordx4 v[88:91], v21, s[20:21]
	global_load_dwordx4 v[92:95], v22, s[20:21]
	global_load_dwordx4 v[96:99], v23, s[20:21]
	global_load_dwordx4 v[100:103], v24, s[20:21]
	global_load_dwordx4 v[104:107], v25, s[20:21]
	global_load_dwordx4 v[108:111], v26, s[20:21]
	global_load_dwordx4 v[112:115], v27, s[20:21]
	global_load_dwordx4 v[116:119], v28, s[20:21]
	global_load_dwordx4 v[120:123], v29, s[20:21]
	global_load_dwordx4 v[124:127], v30, s[20:21]
	global_load_dwordx4 v[128:131], v31, s[20:21]
	global_load_dwordx4 v[132:135], v32, s[20:21]
	global_load_dwordx4 v[136:139], v33, s[20:21]
	global_load_dwordx4 v[140:143], v34, s[20:21]
	global_load_dwordx4 v[144:147], v35, s[20:21]
	global_load_dwordx4 v[148:151], v36, s[20:21]
	global_load_dwordx4 v[152:155], v37, s[20:21]
	global_load_dwordx4 v[156:159], v38, s[20:21]
	global_load_dwordx4 v[160:163], v39, s[20:21]
	global_load_dwordx4 v[164:167], v40, s[20:21]
	global_load_dwordx4 v[168:171], v41, s[20:21]
	global_load_dwordx4 v[172:175], v42, s[20:21]
	global_load_dwordx4 v[176:179], v43, s[20:21]
	global_load_dwordx4 v[180:183], v44, s[20:21]
	global_load_dwordx4 v[184:187], v45, s[20:21]
	global_load_dwordx4 v[190:193], v46, s[20:21]
	global_load_dwordx4 v[194:197], v47, s[20:21]
	global_load_dwordx4 v[198:201], v48, s[20:21]
	global_load_dwordx4 v[202:205], v49, s[20:21]
	global_load_dwordx4 v[206:209], v50, s[20:21]
	global_load_dwordx4 v[210:213], v51, s[20:21]
	v_mov_b32_e32 v52, 0
	v_mov_b32_e32 v53, 0
	v_mov_b32_e32 v54, 0
	v_mov_b32_e32 v55, 0
	v_mov_b32_e32 v56, 0
	v_mov_b32_e32 v57, 0
	v_mov_b32_e32 v58, 0
	v_mov_b32_e32 v59, 0
	v_mov_b32_e32 v60, 0
	v_mov_b32_e32 v61, 0
	v_mov_b32_e32 v62, 0
	v_mov_b32_e32 v63, 0
	v_mov_b32_e32 v64, 0
	v_mov_b32_e32 v65, 0
	v_mov_b32_e32 v66, 0
	v_mov_b32_e32 v67, 0
	v_mov_b32_e32 v68, 0
	v_mov_b32_e32 v69, 0
	v_mov_b32_e32 v70, 0
	v_mov_b32_e32 v71, 0
	v_mov_b32_e32 v72, 0
	v_mov_b32_e32 v73, 0
	v_mov_b32_e32 v74, 0
	v_mov_b32_e32 v75, 0
	v_mov_b32_e32 v76, 0
	v_mov_b32_e32 v77, 0
	v_mov_b32_e32 v78, 0
	v_mov_b32_e32 v79, 0
	v_mov_b32_e32 v80, 0
	v_mov_b32_e32 v81, 0
	v_mov_b32_e32 v82, 0
	v_mov_b32_e32 v83, 0
	s_waitcnt vmcnt(31)
	v_dot4c_i32_i8_e32 v52, v84, v12
	s_waitcnt vmcnt(30)
	v_dot4c_i32_i8_e32 v53, v88, v12
	s_waitcnt vmcnt(29)
	v_dot4c_i32_i8_e32 v54, v92, v12
	s_waitcnt vmcnt(28)
	v_dot4c_i32_i8_e32 v55, v96, v12
	s_waitcnt vmcnt(27)
	v_dot4c_i32_i8_e32 v56, v100, v12
	s_waitcnt vmcnt(26)
	v_dot4c_i32_i8_e32 v57, v104, v12
	s_waitcnt vmcnt(25)
	v_dot4c_i32_i8_e32 v58, v108, v12
	s_waitcnt vmcnt(24)
	v_dot4c_i32_i8_e32 v59, v112, v12
	s_waitcnt vmcnt(23)
	v_dot4c_i32_i8_e32 v60, v116, v12
	s_waitcnt vmcnt(22)
	v_dot4c_i32_i8_e32 v61, v120, v12
	s_waitcnt vmcnt(21)
	v_dot4c_i32_i8_e32 v62, v124, v12
	s_waitcnt vmcnt(20)
	v_dot4c_i32_i8_e32 v63, v128, v12
	s_waitcnt vmcnt(19)
	v_dot4c_i32_i8_e32 v64, v132, v12
	s_waitcnt vmcnt(18)
	v_dot4c_i32_i8_e32 v65, v136, v12
	s_waitcnt vmcnt(17)
	v_dot4c_i32_i8_e32 v66, v140, v12
	s_waitcnt vmcnt(16)
	v_dot4c_i32_i8_e32 v67, v144, v12
	v_dot4c_i32_i8_e32 v52, v85, v13
	v_dot4c_i32_i8_e32 v53, v89, v13
	v_dot4c_i32_i8_e32 v54, v93, v13
	v_dot4c_i32_i8_e32 v55, v97, v13
	v_dot4c_i32_i8_e32 v56, v101, v13
	v_dot4c_i32_i8_e32 v57, v105, v13
	v_dot4c_i32_i8_e32 v58, v109, v13
	v_dot4c_i32_i8_e32 v59, v113, v13
	v_dot4c_i32_i8_e32 v60, v117, v13
	v_dot4c_i32_i8_e32 v61, v121, v13
	v_dot4c_i32_i8_e32 v62, v125, v13
	v_dot4c_i32_i8_e32 v63, v129, v13
	v_dot4c_i32_i8_e32 v64, v133, v13
	v_dot4c_i32_i8_e32 v65, v137, v13
	v_dot4c_i32_i8_e32 v66, v141, v13
	v_dot4c_i32_i8_e32 v67, v145, v13
	v_dot4c_i32_i8_e32 v52, v86, v14
	v_dot4c_i32_i8_e32 v53, v90, v14
	v_dot4c_i32_i8_e32 v54, v94, v14
	v_dot4c_i32_i8_e32 v55, v98, v14
	v_dot4c_i32_i8_e32 v56, v102, v14
	v_dot4c_i32_i8_e32 v57, v106, v14
	v_dot4c_i32_i8_e32 v58, v110, v14
	v_dot4c_i32_i8_e32 v59, v114, v14
	v_dot4c_i32_i8_e32 v60, v118, v14
	v_dot4c_i32_i8_e32 v61, v122, v14
	v_dot4c_i32_i8_e32 v62, v126, v14
	v_dot4c_i32_i8_e32 v63, v130, v14
	v_dot4c_i32_i8_e32 v64, v134, v14
	v_dot4c_i32_i8_e32 v65, v138, v14
	v_dot4c_i32_i8_e32 v66, v142, v14
	v_dot4c_i32_i8_e32 v67, v146, v14
	v_dot4c_i32_i8_e32 v52, v87, v15
	v_dot4c_i32_i8_e32 v53, v91, v15
	v_dot4c_i32_i8_e32 v54, v95, v15
	v_dot4c_i32_i8_e32 v55, v99, v15
	v_dot4c_i32_i8_e32 v56, v103, v15
	v_dot4c_i32_i8_e32 v57, v107, v15
	v_dot4c_i32_i8_e32 v58, v111, v15
	v_dot4c_i32_i8_e32 v59, v115, v15
	v_dot4c_i32_i8_e32 v60, v119, v15
	v_dot4c_i32_i8_e32 v61, v123, v15
	v_dot4c_i32_i8_e32 v62, v127, v15
	v_dot4c_i32_i8_e32 v63, v131, v15
	v_dot4c_i32_i8_e32 v64, v135, v15
	v_dot4c_i32_i8_e32 v65, v139, v15
	v_dot4c_i32_i8_e32 v66, v143, v15
	v_dot4c_i32_i8_e32 v67, v147, v15
	ds_write2_b32 v5, v10, v11 offset0:4 offset1:20
	s_waitcnt lgkmcnt(0)
; DI void phase9(const Params& p, char* smem, int rep) {
;     ...
;         for (int q = 0; q < 4; ++q) { const int4 v = *(const int4*)(lw + g * 32 + batch * 16 + q * 4); ida[q * 4] = v.x; ida[q * 4 + 1] = v.y; ida[q * 4 + 2] = v.z; ida[q * 4 + 3] = v.w; }
;         u32x4 rows[16];
; #pragma unroll
;         for (int k = 0; k < 16; ++k) rows[k] = *(const u32x4*)(ub + (size_t)ida[k] * 2048);
;         int part[16];
; #pragma unroll
;         for (int k = 0; k < 16; ++k) {
;           int acc = 0;
; #pragma unroll
;           for (int d = 0; d < 4; ++d) acc = __builtin_amdgcn_sdot4((int)rows[k][d], (int)hq[d], acc, false);
;           part[k] = acc;
;         }
;         int q8[8], q4[4], q2[2];
; #pragma unroll
;         for (int k = 0; k < 8; ++k) q8[k] = (b3 ? part[8 + k] : part[k]) + __shfl_xor(b3 ? part[k] : part[8 + k], 8);
; #pragma unroll
;         for (int k = 0; k < 4; ++k) q4[k] = (b2 ? q8[4 + k] : q8[k]) + __shfl_xor(b2 ? q8[k] : q8[4 + k], 4);
; #pragma unroll
;         for (int k = 0; k < 2; ++k) q2[k] = (b1 ? q4[2 + k] : q4[k]) + __shfl_xor(b1 ? q4[k] : q4[2 + k], 2);
;         const int rr = (b0 ? q2[1] : q2[0]) + __shfl_xor(b0 ? q2[0] : q2[1], 1);
;         PA[((size_t)s * T_ + tok) * 128 + 4 * (batch * 16 + l15) + g] = rr;
	ds_read_b128 v[20:23], v6 offset:16
	ds_read_b128 v[24:27], v6 offset:32
	ds_read_b128 v[28:31], v6 offset:48
	ds_read_b128 v[32:35], v6 offset:64
	ds_read_b128 v[36:39], v6 offset:80
	ds_read_b128 v[40:43], v6 offset:96
	ds_read_b128 v[44:47], v6 offset:112
	ds_read_b128 v[48:51], v6 offset:128
	v_add_u32_dpp v84, v52, v52 row_ror:8 row_mask:0xf bank_mask:0x3
	v_add_u32_dpp v84, v60, v60 row_ror:8 row_mask:0xf bank_mask:0xc
	v_add_u32_dpp v85, v53, v53 row_ror:8 row_mask:0xf bank_mask:0x3
	v_add_u32_dpp v85, v61, v61 row_ror:8 row_mask:0xf bank_mask:0xc
	v_add_u32_dpp v86, v54, v54 row_ror:8 row_mask:0xf bank_mask:0x3
	v_add_u32_dpp v86, v62, v62 row_ror:8 row_mask:0xf bank_mask:0xc
	v_add_u32_dpp v87, v55, v55 row_ror:8 row_mask:0xf bank_mask:0x3
	v_add_u32_dpp v87, v63, v63 row_ror:8 row_mask:0xf bank_mask:0xc
	v_add_u32_dpp v88, v56, v56 row_ror:8 row_mask:0xf bank_mask:0x3
	v_add_u32_dpp v88, v64, v64 row_ror:8 row_mask:0xf bank_mask:0xc
	v_add_u32_dpp v89, v57, v57 row_ror:8 row_mask:0xf bank_mask:0x3
	v_add_u32_dpp v89, v65, v65 row_ror:8 row_mask:0xf bank_mask:0xc
	v_add_u32_dpp v90, v58, v58 row_ror:8 row_mask:0xf bank_mask:0x3
	v_add_u32_dpp v90, v66, v66 row_ror:8 row_mask:0xf bank_mask:0xc
	v_add_u32_dpp v91, v59, v59 row_ror:8 row_mask:0xf bank_mask:0x3
	v_add_u32_dpp v91, v67, v67 row_ror:8 row_mask:0xf bank_mask:0xc
	v_add_u32_dpp v92, v84, v84 row_half_mirror row_mask:0xf bank_mask:0x5
	v_add_u32_dpp v92, v88, v88 row_half_mirror row_mask:0xf bank_mask:0xa
	v_add_u32_dpp v93, v85, v85 row_half_mirror row_mask:0xf bank_mask:0x5
	v_add_u32_dpp v93, v89, v89 row_half_mirror row_mask:0xf bank_mask:0xa
	v_add_u32_dpp v94, v86, v86 row_half_mirror row_mask:0xf bank_mask:0x5
	v_add_u32_dpp v94, v90, v90 row_half_mirror row_mask:0xf bank_mask:0xa
	v_add_u32_dpp v95, v87, v87 row_half_mirror row_mask:0xf bank_mask:0x5
	v_add_u32_dpp v95, v91, v91 row_half_mirror row_mask:0xf bank_mask:0xa
	v_add_u32_dpp v96, v92, v92 quad_perm:[2,3,0,1] row_mask:0xf bank_mask:0xf
	v_add_u32_dpp v97, v93, v93 quad_perm:[2,3,0,1] row_mask:0xf bank_mask:0xf
	v_add_u32_dpp v98, v94, v94 quad_perm:[2,3,0,1] row_mask:0xf bank_mask:0xf
	s_nop 0
	v_add_u32_dpp v99, v95, v95 quad_perm:[2,3,0,1] row_mask:0xf bank_mask:0xf
	v_cndmask_b32_e64 v100, v98, v96, s[2:3]
	v_cndmask_b32_e64 v101, v99, v97, s[2:3]
	v_add_u32_e32 v214, s46, v4
	s_nop 1
	v_add_u32_dpp v102, v100, v100 quad_perm:[1,0,3,2] row_mask:0xf bank_mask:0xf
	v_add_u32_dpp v103, v101, v101 quad_perm:[1,0,3,2] row_mask:0xf bank_mask:0xf
	v_cndmask_b32_e64 v104, v103, v102, s[4:5]
	global_store_dword v214, v104, s[14:15]
	s_waitcnt vmcnt(16)
	v_dot4c_i32_i8_e32 v68, v148, v12
	s_waitcnt vmcnt(15)
	v_dot4c_i32_i8_e32 v69, v152, v12
	s_waitcnt vmcnt(14)
	v_dot4c_i32_i8_e32 v70, v156, v12
	s_waitcnt vmcnt(13)
	v_dot4c_i32_i8_e32 v71, v160, v12
	s_waitcnt vmcnt(12)
	v_dot4c_i32_i8_e32 v72, v164, v12
	s_waitcnt vmcnt(11)
	v_dot4c_i32_i8_e32 v73, v168, v12
	s_waitcnt vmcnt(10)
	v_dot4c_i32_i8_e32 v74, v172, v12
	s_waitcnt vmcnt(9)
	v_dot4c_i32_i8_e32 v75, v176, v12
	s_waitcnt vmcnt(8)
	v_dot4c_i32_i8_e32 v76, v180, v12
	s_waitcnt vmcnt(7)
	v_dot4c_i32_i8_e32 v77, v184, v12
	s_waitcnt vmcnt(6)
	v_dot4c_i32_i8_e32 v78, v190, v12
	s_waitcnt vmcnt(5)
	v_dot4c_i32_i8_e32 v79, v194, v12
	s_waitcnt vmcnt(4)
	v_dot4c_i32_i8_e32 v80, v198, v12
	s_waitcnt vmcnt(3)
	v_dot4c_i32_i8_e32 v81, v202, v12
	s_waitcnt vmcnt(2)
	v_dot4c_i32_i8_e32 v82, v206, v12
	s_waitcnt vmcnt(1)
	v_dot4c_i32_i8_e32 v83, v210, v12
	v_dot4c_i32_i8_e32 v68, v149, v13
	v_dot4c_i32_i8_e32 v69, v153, v13
	v_dot4c_i32_i8_e32 v70, v157, v13
	v_dot4c_i32_i8_e32 v71, v161, v13
	v_dot4c_i32_i8_e32 v72, v165, v13
	v_dot4c_i32_i8_e32 v73, v169, v13
	v_dot4c_i32_i8_e32 v74, v173, v13
	v_dot4c_i32_i8_e32 v75, v177, v13
	v_dot4c_i32_i8_e32 v76, v181, v13
	v_dot4c_i32_i8_e32 v77, v185, v13
	v_dot4c_i32_i8_e32 v78, v191, v13
	v_dot4c_i32_i8_e32 v79, v195, v13
	v_dot4c_i32_i8_e32 v80, v199, v13
	v_dot4c_i32_i8_e32 v81, v203, v13
	v_dot4c_i32_i8_e32 v82, v207, v13
	v_dot4c_i32_i8_e32 v83, v211, v13
	v_dot4c_i32_i8_e32 v68, v150, v14
	v_dot4c_i32_i8_e32 v69, v154, v14
	v_dot4c_i32_i8_e32 v70, v158, v14
	v_dot4c_i32_i8_e32 v71, v162, v14
	v_dot4c_i32_i8_e32 v72, v166, v14
	v_dot4c_i32_i8_e32 v73, v170, v14
	v_dot4c_i32_i8_e32 v74, v174, v14
	v_dot4c_i32_i8_e32 v75, v178, v14
	v_dot4c_i32_i8_e32 v76, v182, v14
	v_dot4c_i32_i8_e32 v77, v186, v14
	v_dot4c_i32_i8_e32 v78, v192, v14
	v_dot4c_i32_i8_e32 v79, v196, v14
	v_dot4c_i32_i8_e32 v80, v200, v14
	v_dot4c_i32_i8_e32 v81, v204, v14
	v_dot4c_i32_i8_e32 v82, v208, v14
	v_dot4c_i32_i8_e32 v83, v212, v14
	v_dot4c_i32_i8_e32 v68, v151, v15
	v_dot4c_i32_i8_e32 v69, v155, v15
	v_dot4c_i32_i8_e32 v70, v159, v15
	v_dot4c_i32_i8_e32 v71, v163, v15
	v_dot4c_i32_i8_e32 v72, v167, v15
	v_dot4c_i32_i8_e32 v73, v171, v15
	v_dot4c_i32_i8_e32 v74, v175, v15
	v_dot4c_i32_i8_e32 v75, v179, v15
	v_dot4c_i32_i8_e32 v76, v183, v15
	v_dot4c_i32_i8_e32 v77, v187, v15
	v_dot4c_i32_i8_e32 v78, v193, v15
	v_dot4c_i32_i8_e32 v79, v197, v15
	v_dot4c_i32_i8_e32 v80, v201, v15
	v_dot4c_i32_i8_e32 v81, v205, v15
	v_dot4c_i32_i8_e32 v82, v209, v15
	v_dot4c_i32_i8_e32 v83, v213, v15
	v_add_u32_dpp v148, v68, v68 row_ror:8 row_mask:0xf bank_mask:0x3
	v_add_u32_dpp v148, v76, v76 row_ror:8 row_mask:0xf bank_mask:0xc
	v_add_u32_dpp v149, v69, v69 row_ror:8 row_mask:0xf bank_mask:0x3
	v_add_u32_dpp v149, v77, v77 row_ror:8 row_mask:0xf bank_mask:0xc
	v_add_u32_dpp v150, v70, v70 row_ror:8 row_mask:0xf bank_mask:0x3
	v_add_u32_dpp v150, v78, v78 row_ror:8 row_mask:0xf bank_mask:0xc
	v_add_u32_dpp v151, v71, v71 row_ror:8 row_mask:0xf bank_mask:0x3
; DI void wave_lds_sync() { asm volatile("s_waitcnt lgkmcnt(0)" ::: "memory"); __builtin_amdgcn_wave_barrier(); }
; DI void phase9(const Params& p, char* smem, int rep) {
;     ...
;       const int tok = __builtin_amdgcn_readfirstlane(c * 16 + w * 4 + t);
;       const int i0 = IDS[(size_t)tok * 128 + lane], i1 = IDS[(size_t)tok * 128 + 64 + lane];
;       const u32x4 hq = *(const u32x4*)(H2Q + (size_t)tok * D_ + s * 256 + l15 * 16);
;       wave_lds_sync();
;       lw[(lane & 3) * 32 + (lane >> 2)] = i0;
;       lw[(lane & 3) * 32 + 16 + (lane >> 2)] = i1;
;       wave_lds_sync();
;       const unsigned char* ub = U8 + s * 256 + l15 * 16;
; #pragma unroll
;       for (int batch = 0; batch < 2; ++batch) {
;         int ida[16];
; #pragma unroll
;         for (int q = 0; q < 4; ++q) { const int4 v = *(const int4*)(lw + g * 32 + batch * 16 + q * 4); ida[q * 4] = v.x; ida[q * 4 + 1] = v.y; ida[q * 4 + 2] = v.z; ida[q * 4 + 3] = v.w; }
;         u32x4 rows[16];
; #pragma unroll
;         for (int k = 0; k < 16; ++k) rows[k] = *(const u32x4*)(ub + (size_t)ida[k] * 2048);
;         int part[16];
; #pragma unroll
;         for (int k = 0; k < 16; ++k) {
;           int acc = 0;
; #pragma unroll
;           for (int d = 0; d < 4; ++d) acc = __builtin_amdgcn_sdot4((int)rows[k][d], (int)hq[d], acc, false);
;           part[k] = acc;
;         }
;         int q8[8], q4[4], q2[2];
; #pragma unroll
;         for (int k = 0; k < 8; ++k) q8[k] = (b3 ? part[8 + k] : part[k]) + __shfl_xor(b3 ? part[k] : part[8 + k], 8);
; #pragma unroll
;         for (int k = 0; k < 4; ++k) q4[k] = (b2 ? q8[4 + k] : q8[k]) + __shfl_xor(b2 ? q8[k] : q8[4 + k], 4);
; #pragma unroll
;         for (int k = 0; k < 2; ++k) q2[k] = (b1 ? q4[2 + k] : q4[k]) + __shfl_xor(b1 ? q4[k] : q4[2 + k], 2);
;         const int rr = (b0 ? q2[1] : q2[0]) + __shfl_xor(b0 ? q2[0] : q2[1], 1);
;         PA[((size_t)s * T_ + tok) * 128 + 4 * (batch * 16 + l15) + g] = rr;
	v_add_u32_dpp v151, v79, v79 row_ror:8 row_mask:0xf bank_mask:0xc
	v_add_u32_dpp v152, v72, v72 row_ror:8 row_mask:0xf bank_mask:0x3
	v_add_u32_dpp v152, v80, v80 row_ror:8 row_mask:0xf bank_mask:0xc
	v_add_u32_dpp v153, v73, v73 row_ror:8 row_mask:0xf bank_mask:0x3
	v_add_u32_dpp v153, v81, v81 row_ror:8 row_mask:0xf bank_mask:0xc
	v_add_u32_dpp v154, v74, v74 row_ror:8 row_mask:0xf bank_mask:0x3
	v_add_u32_dpp v154, v82, v82 row_ror:8 row_mask:0xf bank_mask:0xc
	v_add_u32_dpp v155, v75, v75 row_ror:8 row_mask:0xf bank_mask:0x3
	v_add_u32_dpp v155, v83, v83 row_ror:8 row_mask:0xf bank_mask:0xc
	v_add_u32_dpp v156, v148, v148 row_half_mirror row_mask:0xf bank_mask:0x5
	v_add_u32_dpp v156, v152, v152 row_half_mirror row_mask:0xf bank_mask:0xa
	v_add_u32_dpp v157, v149, v149 row_half_mirror row_mask:0xf bank_mask:0x5
	v_add_u32_dpp v157, v153, v153 row_half_mirror row_mask:0xf bank_mask:0xa
	v_add_u32_dpp v158, v150, v150 row_half_mirror row_mask:0xf bank_mask:0x5
	v_add_u32_dpp v158, v154, v154 row_half_mirror row_mask:0xf bank_mask:0xa
	v_add_u32_dpp v159, v151, v151 row_half_mirror row_mask:0xf bank_mask:0x5
	v_add_u32_dpp v159, v155, v155 row_half_mirror row_mask:0xf bank_mask:0xa
	v_add_u32_dpp v160, v156, v156 quad_perm:[2,3,0,1] row_mask:0xf bank_mask:0xf
	v_add_u32_dpp v161, v157, v157 quad_perm:[2,3,0,1] row_mask:0xf bank_mask:0xf
	v_add_u32_dpp v162, v158, v158 quad_perm:[2,3,0,1] row_mask:0xf bank_mask:0xf
	s_nop 0
	v_add_u32_dpp v163, v159, v159 quad_perm:[2,3,0,1] row_mask:0xf bank_mask:0xf
	v_cndmask_b32_e64 v164, v162, v160, s[2:3]
	v_cndmask_b32_e64 v165, v163, v161, s[2:3]
	s_nop 0
	s_nop 1
	v_add_u32_dpp v166, v164, v164 quad_perm:[1,0,3,2] row_mask:0xf bank_mask:0xf
	v_add_u32_dpp v167, v165, v165 quad_perm:[1,0,3,2] row_mask:0xf bank_mask:0xf
	v_cndmask_b32_e64 v168, v167, v166, s[4:5]
	global_store_dword v214, v168, s[14:15] offset:256 nt
	s_add_i32 s36, s34, 3
	s_lshl_b32 s46, s36, 9
	s_add_i32 s46, s46, s24
	s_add_i32 s37, s34, 4
	s_add_i32 s51, s48, 1
	s_cmp_lt_u32 s51, s49
	s_cselect_b32 s37, s37, 8192
	s_cmp_lt_u32 s37, 8192
	s_cselect_b32 s37, s37, 0
	s_lshl_b32 s47, s37, 9
	s_add_u32 s42, s6, s47
	s_addc_u32 s43, s7, 0
	s_lshl_b32 s47, s37, 11
	s_add_u32 s44, s22, s47
	s_addc_u32 s45, s23, 0
	global_load_dword v10, v3, s[42:43]
	global_load_dword v11, v3, s[42:43] offset:256
	global_load_dwordx4 v[12:15], v2, s[44:45]
	s_waitcnt lgkmcnt(0)
	v_lshl_add_u32 v20, v20, 11, v2
	v_lshl_add_u32 v21, v21, 11, v2
	v_lshl_add_u32 v22, v22, 11, v2
	v_lshl_add_u32 v23, v23, 11, v2
	v_lshl_add_u32 v24, v24, 11, v2
	v_lshl_add_u32 v25, v25, 11, v2
	v_lshl_add_u32 v26, v26, 11, v2
	v_lshl_add_u32 v27, v27, 11, v2
	v_lshl_add_u32 v28, v28, 11, v2
	v_lshl_add_u32 v29, v29, 11, v2
	v_lshl_add_u32 v30, v30, 11, v2
	v_lshl_add_u32 v31, v31, 11, v2
	v_lshl_add_u32 v32, v32, 11, v2
	v_lshl_add_u32 v33, v33, 11, v2
	v_lshl_add_u32 v34, v34, 11, v2
	v_lshl_add_u32 v35, v35, 11, v2
	v_lshl_add_u32 v36, v36, 11, v2
	v_lshl_add_u32 v37, v37, 11, v2
	v_lshl_add_u32 v38, v38, 11, v2
	v_lshl_add_u32 v39, v39, 11, v2
	v_lshl_add_u32 v40, v40, 11, v2
	v_lshl_add_u32 v41, v41, 11, v2
	v_lshl_add_u32 v42, v42, 11, v2
	v_lshl_add_u32 v43, v43, 11, v2
	v_lshl_add_u32 v44, v44, 11, v2
	v_lshl_add_u32 v45, v45, 11, v2
	v_lshl_add_u32 v46, v46, 11, v2
	v_lshl_add_u32 v47, v47, 11, v2
	v_lshl_add_u32 v48, v48, 11, v2
	v_lshl_add_u32 v49, v49, 11, v2
	v_lshl_add_u32 v50, v50, 11, v2
	v_lshl_add_u32 v51, v51, 11, v2
	global_load_dwordx4 v[84:87], v20, s[20:21]
	global_load_dwordx4 v[88:91], v21, s[20:21]
	global_load_dwordx4 v[92:95], v22, s[20:21]
	global_load_dwordx4 v[96:99], v23, s[20:21]
	global_load_dwordx4 v[100:103], v24, s[20:21]
	global_load_dwordx4 v[104:107], v25, s[20:21]
	global_load_dwordx4 v[108:111], v26, s[20:21]
	global_load_dwordx4 v[112:115], v27, s[20:21]
	global_load_dwordx4 v[116:119], v28, s[20:21]
	global_load_dwordx4 v[120:123], v29, s[20:21]
	global_load_dwordx4 v[124:127], v30, s[20:21]
	global_load_dwordx4 v[128:131], v31, s[20:21]
	global_load_dwordx4 v[132:135], v32, s[20:21]
	global_load_dwordx4 v[136:139], v33, s[20:21]
	global_load_dwordx4 v[140:143], v34, s[20:21]
	global_load_dwordx4 v[144:147], v35, s[20:21]
	global_load_dwordx4 v[148:151], v36, s[20:21]
	global_load_dwordx4 v[152:155], v37, s[20:21]
	global_load_dwordx4 v[156:159], v38, s[20:21]
	global_load_dwordx4 v[160:163], v39, s[20:21]
	global_load_dwordx4 v[164:167], v40, s[20:21]
	global_load_dwordx4 v[168:171], v41, s[20:21]
	global_load_dwordx4 v[172:175], v42, s[20:21]
	global_load_dwordx4 v[176:179], v43, s[20:21]
	global_load_dwordx4 v[180:183], v44, s[20:21]
	global_load_dwordx4 v[184:187], v45, s[20:21]
	global_load_dwordx4 v[190:193], v46, s[20:21]
	global_load_dwordx4 v[194:197], v47, s[20:21]
	global_load_dwordx4 v[198:201], v48, s[20:21]
	global_load_dwordx4 v[202:205], v49, s[20:21]
	global_load_dwordx4 v[206:209], v50, s[20:21]
	global_load_dwordx4 v[210:213], v51, s[20:21]
	v_mov_b32_e32 v52, 0
	v_mov_b32_e32 v53, 0
	v_mov_b32_e32 v54, 0
	v_mov_b32_e32 v55, 0
	v_mov_b32_e32 v56, 0
	v_mov_b32_e32 v57, 0
	v_mov_b32_e32 v58, 0
	v_mov_b32_e32 v59, 0
	v_mov_b32_e32 v60, 0
	v_mov_b32_e32 v61, 0
	v_mov_b32_e32 v62, 0
	v_mov_b32_e32 v63, 0
	v_mov_b32_e32 v64, 0
	v_mov_b32_e32 v65, 0
	v_mov_b32_e32 v66, 0
	v_mov_b32_e32 v67, 0
	v_mov_b32_e32 v68, 0
	v_mov_b32_e32 v69, 0
	v_mov_b32_e32 v70, 0
	v_mov_b32_e32 v71, 0
	v_mov_b32_e32 v72, 0
	v_mov_b32_e32 v73, 0
	v_mov_b32_e32 v74, 0
	v_mov_b32_e32 v75, 0
	v_mov_b32_e32 v76, 0
	v_mov_b32_e32 v77, 0
	v_mov_b32_e32 v78, 0
	v_mov_b32_e32 v79, 0
	v_mov_b32_e32 v80, 0
	v_mov_b32_e32 v81, 0
	v_mov_b32_e32 v82, 0
	v_mov_b32_e32 v83, 0
	s_waitcnt vmcnt(31)
; DI void phase9(const Params& p, char* smem, int rep) {
;     ...
;         for (int q = 0; q < 4; ++q) { const int4 v = *(const int4*)(lw + g * 32 + batch * 16 + q * 4); ida[q * 4] = v.x; ida[q * 4 + 1] = v.y; ida[q * 4 + 2] = v.z; ida[q * 4 + 3] = v.w; }
;         u32x4 rows[16];
; #pragma unroll
;         for (int k = 0; k < 16; ++k) rows[k] = *(const u32x4*)(ub + (size_t)ida[k] * 2048);
;         int part[16];
; #pragma unroll
;         for (int k = 0; k < 16; ++k) {
;           int acc = 0;
; #pragma unroll
;           for (int d = 0; d < 4; ++d) acc = __builtin_amdgcn_sdot4((int)rows[k][d], (int)hq[d], acc, false);
;           part[k] = acc;
;         }
;         int q8[8], q4[4], q2[2];
; #pragma unroll
;         for (int k = 0; k < 8; ++k) q8[k] = (b3 ? part[8 + k] : part[k]) + __shfl_xor(b3 ? part[k] : part[8 + k], 8);
; #pragma unroll
;         for (int k = 0; k < 4; ++k) q4[k] = (b2 ? q8[4 + k] : q8[k]) + __shfl_xor(b2 ? q8[k] : q8[4 + k], 4);
; #pragma unroll
;         for (int k = 0; k < 2; ++k) q2[k] = (b1 ? q4[2 + k] : q4[k]) + __shfl_xor(b1 ? q4[k] : q4[2 + k], 2);
;         const int rr = (b0 ? q2[1] : q2[0]) + __shfl_xor(b0 ? q2[0] : q2[1], 1);
;         PA[((size_t)s * T_ + tok) * 128 + 4 * (batch * 16 + l15) + g] = rr;
	v_dot4c_i32_i8_e32 v52, v84, v16
	s_waitcnt vmcnt(30)
	v_dot4c_i32_i8_e32 v53, v88, v16
	s_waitcnt vmcnt(29)
	v_dot4c_i32_i8_e32 v54, v92, v16
	s_waitcnt vmcnt(28)
	v_dot4c_i32_i8_e32 v55, v96, v16
	s_waitcnt vmcnt(27)
	v_dot4c_i32_i8_e32 v56, v100, v16
	s_waitcnt vmcnt(26)
	v_dot4c_i32_i8_e32 v57, v104, v16
	s_waitcnt vmcnt(25)
	v_dot4c_i32_i8_e32 v58, v108, v16
	s_waitcnt vmcnt(24)
	v_dot4c_i32_i8_e32 v59, v112, v16
	s_waitcnt vmcnt(23)
	v_dot4c_i32_i8_e32 v60, v116, v16
	s_waitcnt vmcnt(22)
	v_dot4c_i32_i8_e32 v61, v120, v16
	s_waitcnt vmcnt(21)
	v_dot4c_i32_i8_e32 v62, v124, v16
	s_waitcnt vmcnt(20)
	v_dot4c_i32_i8_e32 v63, v128, v16
	s_waitcnt vmcnt(19)
	v_dot4c_i32_i8_e32 v64, v132, v16
	s_waitcnt vmcnt(18)
	v_dot4c_i32_i8_e32 v65, v136, v16
	s_waitcnt vmcnt(17)
	v_dot4c_i32_i8_e32 v66, v140, v16
	s_waitcnt vmcnt(16)
	v_dot4c_i32_i8_e32 v67, v144, v16
	v_dot4c_i32_i8_e32 v52, v85, v17
	v_dot4c_i32_i8_e32 v53, v89, v17
	v_dot4c_i32_i8_e32 v54, v93, v17
	v_dot4c_i32_i8_e32 v55, v97, v17
	v_dot4c_i32_i8_e32 v56, v101, v17
	v_dot4c_i32_i8_e32 v57, v105, v17
	v_dot4c_i32_i8_e32 v58, v109, v17
	v_dot4c_i32_i8_e32 v59, v113, v17
	v_dot4c_i32_i8_e32 v60, v117, v17
	v_dot4c_i32_i8_e32 v61, v121, v17
	v_dot4c_i32_i8_e32 v62, v125, v17
	v_dot4c_i32_i8_e32 v63, v129, v17
	v_dot4c_i32_i8_e32 v64, v133, v17
	v_dot4c_i32_i8_e32 v65, v137, v17
	v_dot4c_i32_i8_e32 v66, v141, v17
	v_dot4c_i32_i8_e32 v67, v145, v17
	v_dot4c_i32_i8_e32 v52, v86, v18
	v_dot4c_i32_i8_e32 v53, v90, v18
	v_dot4c_i32_i8_e32 v54, v94, v18
	v_dot4c_i32_i8_e32 v55, v98, v18
	v_dot4c_i32_i8_e32 v56, v102, v18
	v_dot4c_i32_i8_e32 v57, v106, v18
	v_dot4c_i32_i8_e32 v58, v110, v18
	v_dot4c_i32_i8_e32 v59, v114, v18
	v_dot4c_i32_i8_e32 v60, v118, v18
	v_dot4c_i32_i8_e32 v61, v122, v18
	v_dot4c_i32_i8_e32 v62, v126, v18
	v_dot4c_i32_i8_e32 v63, v130, v18
	v_dot4c_i32_i8_e32 v64, v134, v18
	v_dot4c_i32_i8_e32 v65, v138, v18
	v_dot4c_i32_i8_e32 v66, v142, v18
	v_dot4c_i32_i8_e32 v67, v146, v18
	v_dot4c_i32_i8_e32 v52, v87, v19
	v_dot4c_i32_i8_e32 v53, v91, v19
	v_dot4c_i32_i8_e32 v54, v95, v19
	v_dot4c_i32_i8_e32 v55, v99, v19
	v_dot4c_i32_i8_e32 v56, v103, v19
	v_dot4c_i32_i8_e32 v57, v107, v19
	v_dot4c_i32_i8_e32 v58, v111, v19
	v_dot4c_i32_i8_e32 v59, v115, v19
	v_dot4c_i32_i8_e32 v60, v119, v19
	v_dot4c_i32_i8_e32 v61, v123, v19
	v_dot4c_i32_i8_e32 v62, v127, v19
	v_dot4c_i32_i8_e32 v63, v131, v19
	v_dot4c_i32_i8_e32 v64, v135, v19
	v_dot4c_i32_i8_e32 v65, v139, v19
	v_dot4c_i32_i8_e32 v66, v143, v19
	v_dot4c_i32_i8_e32 v67, v147, v19
	ds_write2_b32 v5, v10, v11 offset0:4 offset1:20
	s_waitcnt lgkmcnt(0)
	ds_read_b128 v[20:23], v6 offset:16
	ds_read_b128 v[24:27], v6 offset:32
	ds_read_b128 v[28:31], v6 offset:48
	ds_read_b128 v[32:35], v6 offset:64
	ds_read_b128 v[36:39], v6 offset:80
	ds_read_b128 v[40:43], v6 offset:96
	ds_read_b128 v[44:47], v6 offset:112
	ds_read_b128 v[48:51], v6 offset:128
	v_add_u32_dpp v84, v52, v52 row_ror:8 row_mask:0xf bank_mask:0x3
	v_add_u32_dpp v84, v60, v60 row_ror:8 row_mask:0xf bank_mask:0xc
	v_add_u32_dpp v85, v53, v53 row_ror:8 row_mask:0xf bank_mask:0x3
	v_add_u32_dpp v85, v61, v61 row_ror:8 row_mask:0xf bank_mask:0xc
	v_add_u32_dpp v86, v54, v54 row_ror:8 row_mask:0xf bank_mask:0x3
	v_add_u32_dpp v86, v62, v62 row_ror:8 row_mask:0xf bank_mask:0xc
	v_add_u32_dpp v87, v55, v55 row_ror:8 row_mask:0xf bank_mask:0x3
	v_add_u32_dpp v87, v63, v63 row_ror:8 row_mask:0xf bank_mask:0xc
	v_add_u32_dpp v88, v56, v56 row_ror:8 row_mask:0xf bank_mask:0x3
	v_add_u32_dpp v88, v64, v64 row_ror:8 row_mask:0xf bank_mask:0xc
	v_add_u32_dpp v89, v57, v57 row_ror:8 row_mask:0xf bank_mask:0x3
	v_add_u32_dpp v89, v65, v65 row_ror:8 row_mask:0xf bank_mask:0xc
	v_add_u32_dpp v90, v58, v58 row_ror:8 row_mask:0xf bank_mask:0x3
	v_add_u32_dpp v90, v66, v66 row_ror:8 row_mask:0xf bank_mask:0xc
	v_add_u32_dpp v91, v59, v59 row_ror:8 row_mask:0xf bank_mask:0x3
	v_add_u32_dpp v91, v67, v67 row_ror:8 row_mask:0xf bank_mask:0xc
	v_add_u32_dpp v92, v84, v84 row_half_mirror row_mask:0xf bank_mask:0x5
	v_add_u32_dpp v92, v88, v88 row_half_mirror row_mask:0xf bank_mask:0xa
	v_add_u32_dpp v93, v85, v85 row_half_mirror row_mask:0xf bank_mask:0x5
	v_add_u32_dpp v93, v89, v89 row_half_mirror row_mask:0xf bank_mask:0xa
	v_add_u32_dpp v94, v86, v86 row_half_mirror row_mask:0xf bank_mask:0x5
	v_add_u32_dpp v94, v90, v90 row_half_mirror row_mask:0xf bank_mask:0xa
	v_add_u32_dpp v95, v87, v87 row_half_mirror row_mask:0xf bank_mask:0x5
	v_add_u32_dpp v95, v91, v91 row_half_mirror row_mask:0xf bank_mask:0xa
	v_add_u32_dpp v96, v92, v92 quad_perm:[2,3,0,1] row_mask:0xf bank_mask:0xf
	v_add_u32_dpp v97, v93, v93 quad_perm:[2,3,0,1] row_mask:0xf bank_mask:0xf
	v_add_u32_dpp v98, v94, v94 quad_perm:[2,3,0,1] row_mask:0xf bank_mask:0xf
	s_nop 0
	v_add_u32_dpp v99, v95, v95 quad_perm:[2,3,0,1] row_mask:0xf bank_mask:0xf
	v_cndmask_b32_e64 v100, v98, v96, s[2:3]
	v_cndmask_b32_e64 v101, v99, v97, s[2:3]
	v_add_u32_e32 v214, s46, v4
	s_nop 1
	v_add_u32_dpp v102, v100, v100 quad_perm:[1,0,3,2] row_mask:0xf bank_mask:0xf
	v_add_u32_dpp v103, v101, v101 quad_perm:[1,0,3,2] row_mask:0xf bank_mask:0xf
	v_cndmask_b32_e64 v104, v103, v102, s[4:5]
	global_store_dword v214, v104, s[14:15]
	s_waitcnt vmcnt(16)
; DI void phase9(const Params& p, char* smem, int rep) {
;     ...
; #pragma unroll
;         for (int k = 0; k < 16; ++k) {
;           int acc = 0;
; #pragma unroll
;           for (int d = 0; d < 4; ++d) acc = __builtin_amdgcn_sdot4((int)rows[k][d], (int)hq[d], acc, false);
;           part[k] = acc;
;         }
;         int q8[8], q4[4], q2[2];
; #pragma unroll
;         for (int k = 0; k < 8; ++k) q8[k] = (b3 ? part[8 + k] : part[k]) + __shfl_xor(b3 ? part[k] : part[8 + k], 8);
; #pragma unroll
;         for (int k = 0; k < 4; ++k) q4[k] = (b2 ? q8[4 + k] : q8[k]) + __shfl_xor(b2 ? q8[k] : q8[4 + k], 4);
; #pragma unroll
;         for (int k = 0; k < 2; ++k) q2[k] = (b1 ? q4[2 + k] : q4[k]) + __shfl_xor(b1 ? q4[k] : q4[2 + k], 2);
;         const int rr = (b0 ? q2[1] : q2[0]) + __shfl_xor(b0 ? q2[0] : q2[1], 1);
;         PA[((size_t)s * T_ + tok) * 128 + 4 * (batch * 16 + l15) + g] = rr;
	v_dot4c_i32_i8_e32 v68, v148, v16
	s_waitcnt vmcnt(15)
	v_dot4c_i32_i8_e32 v69, v152, v16
	s_waitcnt vmcnt(14)
	v_dot4c_i32_i8_e32 v70, v156, v16
	s_waitcnt vmcnt(13)
	v_dot4c_i32_i8_e32 v71, v160, v16
	s_waitcnt vmcnt(12)
	v_dot4c_i32_i8_e32 v72, v164, v16
	s_waitcnt vmcnt(11)
	v_dot4c_i32_i8_e32 v73, v168, v16
	s_waitcnt vmcnt(10)
	v_dot4c_i32_i8_e32 v74, v172, v16
	s_waitcnt vmcnt(9)
	v_dot4c_i32_i8_e32 v75, v176, v16
	s_waitcnt vmcnt(8)
	v_dot4c_i32_i8_e32 v76, v180, v16
	s_waitcnt vmcnt(7)
	v_dot4c_i32_i8_e32 v77, v184, v16
	s_waitcnt vmcnt(6)
	v_dot4c_i32_i8_e32 v78, v190, v16
	s_waitcnt vmcnt(5)
	v_dot4c_i32_i8_e32 v79, v194, v16
	s_waitcnt vmcnt(4)
	v_dot4c_i32_i8_e32 v80, v198, v16
	s_waitcnt vmcnt(3)
	v_dot4c_i32_i8_e32 v81, v202, v16
	s_waitcnt vmcnt(2)
	v_dot4c_i32_i8_e32 v82, v206, v16
	s_waitcnt vmcnt(1)
	v_dot4c_i32_i8_e32 v83, v210, v16
	v_dot4c_i32_i8_e32 v68, v149, v17
	v_dot4c_i32_i8_e32 v69, v153, v17
	v_dot4c_i32_i8_e32 v70, v157, v17
	v_dot4c_i32_i8_e32 v71, v161, v17
	v_dot4c_i32_i8_e32 v72, v165, v17
	v_dot4c_i32_i8_e32 v73, v169, v17
	v_dot4c_i32_i8_e32 v74, v173, v17
	v_dot4c_i32_i8_e32 v75, v177, v17
	v_dot4c_i32_i8_e32 v76, v181, v17
	v_dot4c_i32_i8_e32 v77, v185, v17
	v_dot4c_i32_i8_e32 v78, v191, v17
	v_dot4c_i32_i8_e32 v79, v195, v17
	v_dot4c_i32_i8_e32 v80, v199, v17
	v_dot4c_i32_i8_e32 v81, v203, v17
	v_dot4c_i32_i8_e32 v82, v207, v17
	v_dot4c_i32_i8_e32 v83, v211, v17
	v_dot4c_i32_i8_e32 v68, v150, v18
	v_dot4c_i32_i8_e32 v69, v154, v18
	v_dot4c_i32_i8_e32 v70, v158, v18
	v_dot4c_i32_i8_e32 v71, v162, v18
	v_dot4c_i32_i8_e32 v72, v166, v18
	v_dot4c_i32_i8_e32 v73, v170, v18
	v_dot4c_i32_i8_e32 v74, v174, v18
	v_dot4c_i32_i8_e32 v75, v178, v18
	v_dot4c_i32_i8_e32 v76, v182, v18
	v_dot4c_i32_i8_e32 v77, v186, v18
	v_dot4c_i32_i8_e32 v78, v192, v18
	v_dot4c_i32_i8_e32 v79, v196, v18
	v_dot4c_i32_i8_e32 v80, v200, v18
	v_dot4c_i32_i8_e32 v81, v204, v18
	v_dot4c_i32_i8_e32 v82, v208, v18
	v_dot4c_i32_i8_e32 v83, v212, v18
	v_dot4c_i32_i8_e32 v68, v151, v19
	v_dot4c_i32_i8_e32 v69, v155, v19
	v_dot4c_i32_i8_e32 v70, v159, v19
	v_dot4c_i32_i8_e32 v71, v163, v19
	v_dot4c_i32_i8_e32 v72, v167, v19
	v_dot4c_i32_i8_e32 v73, v171, v19
	v_dot4c_i32_i8_e32 v74, v175, v19
	v_dot4c_i32_i8_e32 v75, v179, v19
	v_dot4c_i32_i8_e32 v76, v183, v19
	v_dot4c_i32_i8_e32 v77, v187, v19
	v_dot4c_i32_i8_e32 v78, v193, v19
	v_dot4c_i32_i8_e32 v79, v197, v19
	v_dot4c_i32_i8_e32 v80, v201, v19
	v_dot4c_i32_i8_e32 v81, v205, v19
	v_dot4c_i32_i8_e32 v82, v209, v19
	v_dot4c_i32_i8_e32 v83, v213, v19
	v_add_u32_dpp v148, v68, v68 row_ror:8 row_mask:0xf bank_mask:0x3
	v_add_u32_dpp v148, v76, v76 row_ror:8 row_mask:0xf bank_mask:0xc
	v_add_u32_dpp v149, v69, v69 row_ror:8 row_mask:0xf bank_mask:0x3
	v_add_u32_dpp v149, v77, v77 row_ror:8 row_mask:0xf bank_mask:0xc
	v_add_u32_dpp v150, v70, v70 row_ror:8 row_mask:0xf bank_mask:0x3
	v_add_u32_dpp v150, v78, v78 row_ror:8 row_mask:0xf bank_mask:0xc
	v_add_u32_dpp v151, v71, v71 row_ror:8 row_mask:0xf bank_mask:0x3
	v_add_u32_dpp v151, v79, v79 row_ror:8 row_mask:0xf bank_mask:0xc
	v_add_u32_dpp v152, v72, v72 row_ror:8 row_mask:0xf bank_mask:0x3
	v_add_u32_dpp v152, v80, v80 row_ror:8 row_mask:0xf bank_mask:0xc
	v_add_u32_dpp v153, v73, v73 row_ror:8 row_mask:0xf bank_mask:0x3
	v_add_u32_dpp v153, v81, v81 row_ror:8 row_mask:0xf bank_mask:0xc
	v_add_u32_dpp v154, v74, v74 row_ror:8 row_mask:0xf bank_mask:0x3
	v_add_u32_dpp v154, v82, v82 row_ror:8 row_mask:0xf bank_mask:0xc
	v_add_u32_dpp v155, v75, v75 row_ror:8 row_mask:0xf bank_mask:0x3
	v_add_u32_dpp v155, v83, v83 row_ror:8 row_mask:0xf bank_mask:0xc
	v_add_u32_dpp v156, v148, v148 row_half_mirror row_mask:0xf bank_mask:0x5
	v_add_u32_dpp v156, v152, v152 row_half_mirror row_mask:0xf bank_mask:0xa
	v_add_u32_dpp v157, v149, v149 row_half_mirror row_mask:0xf bank_mask:0x5
	v_add_u32_dpp v157, v153, v153 row_half_mirror row_mask:0xf bank_mask:0xa
	v_add_u32_dpp v158, v150, v150 row_half_mirror row_mask:0xf bank_mask:0x5
	v_add_u32_dpp v158, v154, v154 row_half_mirror row_mask:0xf bank_mask:0xa
	v_add_u32_dpp v159, v151, v151 row_half_mirror row_mask:0xf bank_mask:0x5
	v_add_u32_dpp v159, v155, v155 row_half_mirror row_mask:0xf bank_mask:0xa
	v_add_u32_dpp v160, v156, v156 quad_perm:[2,3,0,1] row_mask:0xf bank_mask:0xf
	v_add_u32_dpp v161, v157, v157 quad_perm:[2,3,0,1] row_mask:0xf bank_mask:0xf
	v_add_u32_dpp v162, v158, v158 quad_perm:[2,3,0,1] row_mask:0xf bank_mask:0xf
	s_nop 0
	v_add_u32_dpp v163, v159, v159 quad_perm:[2,3,0,1] row_mask:0xf bank_mask:0xf
	v_cndmask_b32_e64 v164, v162, v160, s[2:3]
	v_cndmask_b32_e64 v165, v163, v161, s[2:3]
	s_nop 0
	s_nop 1
	v_add_u32_dpp v166, v164, v164 quad_perm:[1,0,3,2] row_mask:0xf bank_mask:0xf
	v_add_u32_dpp v167, v165, v165 quad_perm:[1,0,3,2] row_mask:0xf bank_mask:0xf
	v_cndmask_b32_e64 v168, v167, v166, s[4:5]
	global_store_dword v214, v168, s[14:15] offset:256 nt
	s_add_i32 s48, s48, 1
	s_add_i32 s34, s34, 4
	s_cmp_lt_u32 s48, s49
	s_cbranch_scc0 .Lp9_chunk_done
	s_cmp_lt_u32 s34, 8192
	s_cbranch_scc1 .Lp9_body
	s_branch .Lp9_slice_next

; DI void phase10(const Params& p) {
;     ...
;   for (int i = blockIdx.x * 256 + threadIdx.x; i < T_ * 128; i += gridDim.x * 256) {
;     int ai = 0;
; #pragma unroll
;     for (int s = 0; s < 8; ++s) ai += PA[(size_t)s * T_ * 128 + i];
;     const int id = IDS[i];
;     const float a = (float)ai * USC[id] * HSC[i >> 7];
;     ACT[i] = 0.5f * a * (1.f + erff(a * 0.70710678118654752f)) * GATE[i] * VSC[id];
;   }
.LBB0_1190:
	v_ashrrev_i32_e32 v3, 31, v2
	v_lshlrev_b64 v[4:5], 2, v[2:3]
	v_lshl_add_u64 v[6:7], s[10:11], 0, v[4:5]
	global_load_dword v6, v[6:7], off
	v_lshl_add_u64 v[10:11], s[4:5], 0, v[4:5]
	v_add_co_u32_e32 v12, vcc, 0x400000, v10
	s_waitcnt vmcnt(0)
	v_ashrrev_i32_e32 v7, 31, v6
	v_addc_co_u32_e32 v13, vcc, 0, v11, vcc
	v_add_co_u32_e32 v14, vcc, 0x800000, v10
	s_nop 1
	v_addc_co_u32_e32 v15, vcc, 0, v11, vcc
	v_add_co_u32_e32 v16, vcc, 0xc00000, v10
	s_nop 1
	v_addc_co_u32_e32 v17, vcc, 0, v11, vcc
	v_add_co_u32_e32 v18, vcc, 0x1000000, v10
	s_nop 1
	v_addc_co_u32_e32 v19, vcc, 0, v11, vcc
	v_add_co_u32_e32 v20, vcc, 0x1400000, v10
	s_nop 1
	v_addc_co_u32_e32 v21, vcc, 0, v11, vcc
	v_add_co_u32_e32 v22, vcc, 0x1800000, v10
	s_nop 1
	v_addc_co_u32_e32 v23, vcc, 0, v11, vcc
	v_add_co_u32_e32 v24, vcc, 0x1c00000, v10
	s_nop 1
	v_addc_co_u32_e32 v25, vcc, 0, v11, vcc
	global_load_dword v3, v[10:11], off nt
	global_load_dword v26, v[12:13], off nt
	global_load_dword v27, v[14:15], off nt
	global_load_dword v28, v[16:17], off nt
	global_load_dword v29, v[18:19], off nt
	global_load_dword v30, v[20:21], off nt
	global_load_dword v31, v[22:23], off nt
	global_load_dword v32, v[24:25], off nt
	v_ashrrev_i32_e32 v10, 7, v2
	v_ashrrev_i32_e32 v11, 31, v10
	v_lshl_add_u64 v[10:11], v[10:11], 2, s[8:9]
	global_load_dword v12, v[10:11], off
	v_lshl_add_u64 v[10:11], v[6:7], 2, s[16:17]
	global_load_dword v10, v[10:11], off
	s_waitcnt vmcnt(8)
	v_add_u32_e32 v3, v26, v3
	s_waitcnt vmcnt(6)
	v_add3_u32 v3, v3, v27, v28
	s_waitcnt vmcnt(4)
	v_add3_u32 v3, v3, v29, v30
	s_waitcnt vmcnt(2)
	v_add3_u32 v3, v3, v31, v32
	v_cvt_f32_i32_e32 v3, v3
	s_waitcnt vmcnt(0)
	v_mul_f32_e32 v3, v10, v3
	v_mul_f32_e32 v3, v3, v12
	v_mul_f32_e32 v10, 0x3f3504f3, v3
	v_cmp_nlt_f32_e64 s[22:23], |v10|, 1.0
	s_and_saveexec_b64 s[40:41], s[22:23]
	s_xor_b64 s[22:23], exec, s[40:41]
	s_cbranch_execz .LBB0_1192
	v_fma_f32 v11, |v10|, s24, v8
	v_fma_f32 v11, |v10|, v11, s25
	v_fma_f32 v11, |v10|, v11, s26
	v_fma_f32 v11, |v10|, v11, s27
	v_fma_f32 v11, |v10|, v11, s28
	v_fma_f32 v11, |v10|, v11, s29
	v_fma_f32 v11, |v10|, v11, |v10|
	v_mul_f32_e32 v12, 0xbfb8aa3b, v11
	v_fma_f32 v13, v11, s30, -v12
	v_rndne_f32_e32 v14, v12
	v_fmac_f32_e32 v13, 0xb2a5705f, v11
	v_sub_f32_e32 v12, v12, v14
	v_add_f32_e32 v12, v12, v13
	v_cvt_i32_f32_e32 v13, v14
	v_exp_f32_e32 v12, v12
	v_cmp_nlt_f32_e32 vcc, s31, v11
	v_ldexp_f32 v12, v12, v13
	s_nop 0
	v_cndmask_b32_e32 v12, 0, v12, vcc
	v_cmp_ngt_f32_e32 vcc, s34, v11
	s_nop 1
	v_cndmask_b32_e32 v11, v9, v12, vcc
	v_sub_f32_e32 v11, 1.0, v11
